# WO and DOWN epilogues: the eight gamma/beta loads issued together (one wait instead of four serialized round trips)
# baseline (speedup 1.0000x reference)
;     __device__ __forceinline__ void operator()(Acc& acc, const Unit& u, int wr, int wc, int fr, int fq) const {
;         const int row0 = u.pm * BM + wr * 64 + fr, colb = u.pn * BM + wc * 64 + 8 * fq;
;         const bool lo = fr < 8; const size_t sbase = (size_t)(row0 - fr + (fr & 7)) * DM + colb + (lo ? 0 : BJ);
;         f32x4 gv[2][2], bv[2][2];
;         if (!x) {
; #pragma unroll
;             for (int bj = 0; bj < 2; ++bj)
; #pragma unroll
;                 for (int n = 0; n < 2; ++n) { gv[bj][n] = *(const f32x4*)(gam + colb + bj * BJ + 4 * n) * DN_ALPHA; bv[bj][n] = *(const f32x4*)(bet + colb + bj * BJ + 4 * n) * DN_ALPHA; }
;         }
;         if (x) {
; #pragma unroll
;             for (int ai = 0; ai < 2; ++ai)
; #pragma unroll
;                 for (int m = 0; m < 4; ++m) { const size_t ro = (size_t)(row0 + ai * HALF + m * 16) * DM + colb; u32x4 dd[2];
; #pragma unroll
;                     for (int bj = 0; bj < 2; ++bj) { const f32x4 r0 = *(const f32x4*)(x + ro + bj * BJ), r1 = *(const f32x4*)(x + ro + bj * BJ + 4);
;                         const f32x4 o0 = r0 * DN_ALPHA + acc[ai][bj][m][0], o1 = r1 * DN_ALPHA + acc[ai][bj][m][1];
;                         const f32x8 o = {o0[0], o0[1], o0[2], o0[3], o1[0], o1[1], o1[2], o1[3]};
;                         dd[bj] = __builtin_bit_cast(u32x4, __builtin_convertvector(o, h16x8)); }
;                     store_pair128(pre + sbase + (size_t)(ai * HALF + m * 16) * DM, (size_t)8 * DM, dd[0], dd[1], lo);
;                     if (m & 1) asm volatile("" ::: "memory"); }
;         } else {
; #pragma unroll
;             for (int ai = 0; ai < 2; ++ai)
; #pragma unroll
;               for (int mp = 0; mp < 4; mp += 2) {
;                 f32x2 ms[2]; h16x8 rr[2][2];
; #pragma unroll
;                 for (int m = 0; m < 2; ++m) { const int row = row0 + ai * HALF + (mp + m) * 16; ms[m] = st[row];
; #pragma unroll
;                     for (int bj = 0; bj < 2; ++bj) rr[m][bj] = *(const h16x8*)(pre + (size_t)row * DM + colb + bj * BJ); }
;                 asm volatile("" ::: "memory");
; #pragma unroll
;                 for (int m = 0; m < 2; ++m) { u32x4 dd[2];
; #pragma unroll
;                     for (int bj = 0; bj < 2; ++bj) { const f32x8 r = __builtin_convertvector(rr[m][bj], f32x8);
;                         const f32x4 r0 = {r[0], r[1], r[2], r[3]}, r1 = {r[4], r[5], r[6], r[7]};
.LBB0_847:
	v_lshl_add_u64 v[182:183], s[6:7], 0, v[172:173]
	global_load_dwordx4 v[132:135], v[182:183], off offset:16
	global_load_dwordx4 v[154:157], v[182:183], off
	v_lshl_add_u64 v[186:187], s[8:9], 0, v[172:173]
	s_mov_b32 s2, 0x3fd744fd
	v_lshl_add_u64 v[206:207], v[170:171], 1, s[88:89]
	v_lshl_add_u64 v[170:171], v[138:139], 3, s[66:67]
	global_load_dwordx4 v[222:225], v[186:187], off offset:16
	global_load_dwordx4 v[226:229], v[186:187], off
	global_load_dwordx4 v[232:235], v[182:183], off offset:144
	global_load_dwordx4 v[236:239], v[182:183], off offset:128
	global_load_dwordx4 v[240:243], v[186:187], off offset:144
	global_load_dwordx4 v[244:247], v[186:187], off offset:128
	s_waitcnt vmcnt(0)
	v_pk_mul_f32 v[188:189], v[132:133], s[2:3] op_sel_hi:[1,0]
	v_pk_mul_f32 v[172:173], v[154:155], s[2:3] op_sel_hi:[1,0]
	v_pk_mul_f32 v[174:175], v[156:157], s[2:3] op_sel_hi:[1,0]
	v_mov_b64_e32 v[154:155], v[222:223]
	v_mov_b64_e32 v[156:157], v[224:225]
	v_mov_b64_e32 v[176:177], v[226:227]
	v_mov_b64_e32 v[178:179], v[228:229]
	v_pk_mul_f32 v[192:193], v[134:135], s[2:3] op_sel_hi:[1,0]
	v_pk_mul_f32 v[194:195], v[154:155], s[2:3] op_sel_hi:[1,0]
	v_pk_mul_f32 v[200:201], v[156:157], s[2:3] op_sel_hi:[1,0]
	v_mov_b64_e32 v[132:133], v[232:233]
	v_mov_b64_e32 v[134:135], v[234:235]
	v_mov_b64_e32 v[154:155], v[236:237]
	v_mov_b64_e32 v[156:157], v[238:239]
	v_pk_mul_f32 v[180:181], v[176:177], s[2:3] op_sel_hi:[1,0]
	v_pk_mul_f32 v[184:185], v[178:179], s[2:3] op_sel_hi:[1,0]
	v_pk_mul_f32 v[190:191], v[132:133], s[2:3] op_sel_hi:[1,0]
	v_pk_mul_f32 v[176:177], v[154:155], s[2:3] op_sel_hi:[1,0]
	v_pk_mul_f32 v[178:179], v[156:157], s[2:3] op_sel_hi:[1,0]
	v_mov_b64_e32 v[154:155], v[240:241]
	v_mov_b64_e32 v[156:157], v[242:243]
	v_mov_b64_e32 v[196:197], v[244:245]
	v_mov_b64_e32 v[198:199], v[246:247]
	v_lshlrev_b64 v[132:133], 12, v[138:139]
	v_lshl_add_u64 v[204:205], v[206:207], 0, v[132:133]
	global_load_dwordx2 v[210:211], v[170:171], off
	v_lshl_add_u64 v[132:133], v[136:137], 3, s[66:67]
	s_waitcnt vmcnt(2)
	v_pk_mul_f32 v[202:203], v[156:157], s[2:3] op_sel_hi:[1,0]
	s_waitcnt vmcnt(1)
	v_pk_mul_f32 v[186:187], v[198:199], s[2:3] op_sel_hi:[1,0]
	v_pk_mul_f32 v[198:199], v[154:155], s[2:3] op_sel_hi:[1,0]
	global_load_dwordx4 v[154:157], v[204:205], off
	global_load_dwordx4 v[222:225], v[204:205], off offset:64
	global_load_dwordx2 v[208:209], v[132:133], off
	v_lshlrev_b64 v[132:133], 12, v[136:137]
	v_lshl_add_u64 v[132:133], v[206:207], 0, v[132:133]
	v_pk_mul_f32 v[182:183], v[196:197], s[2:3] op_sel_hi:[1,0]
	v_pk_mul_f32 v[196:197], v[134:135], s[2:3] op_sel_hi:[1,0]
	global_load_dwordx4 v[136:139], v[132:133], off
	s_nop 0
	global_load_dwordx4 v[132:135], v[132:133], off offset:64
	s_mov_b32 s2, 0x8000
	s_waitcnt vmcnt(4)
	v_cvt_f32_f16_sdwa v98, v154 dst_sel:DWORD dst_unused:UNUSED_PAD src0_sel:WORD_1
	v_cvt_f32_f16_e32 v228, v154
	v_cvt_f32_f16_sdwa v227, v155 dst_sel:DWORD dst_unused:UNUSED_PAD src0_sel:WORD_1
	v_cvt_f32_f16_e32 v226, v155
	v_cvt_f32_f16_sdwa v229, v156 dst_sel:DWORD dst_unused:UNUSED_PAD src0_sel:WORD_1
	v_cvt_f32_f16_e32 v156, v156
	v_cvt_f32_f16_sdwa v155, v157 dst_sel:DWORD dst_unused:UNUSED_PAD src0_sel:WORD_1
	v_cvt_f32_f16_e32 v154, v157
	v_sub_f32_e32 v157, v229, v210
	v_sub_f32_e32 v156, v156, v210
	v_sub_f32_e32 v155, v155, v210
	v_sub_f32_e32 v154, v154, v210
	v_sub_f32_e32 v226, v226, v210
	v_sub_f32_e32 v227, v227, v210
	v_pk_mul_f32 v[226:227], v[210:211], v[226:227] op_sel:[1,0]
	v_pk_mul_f32 v[156:157], v[210:211], v[156:157] op_sel:[1,0]
	v_pk_mul_f32 v[154:155], v[210:211], v[154:155] op_sel:[1,0]
	v_sub_f32_e32 v228, v228, v210
	v_sub_f32_e32 v229, v98, v210
	v_pk_fma_f32 v[154:155], v[192:193], v[154:155], v[200:201]
	v_pk_fma_f32 v[156:157], v[188:189], v[156:157], v[194:195]
	v_pk_fma_f32 v[226:227], v[174:175], v[226:227], v[184:185]
	v_pk_mul_f32 v[228:229], v[210:211], v[228:229] op_sel:[1,0]
	v_pk_add_f32 v[130:131], v[130:131], v[226:227]
	v_pk_add_f32 v[124:125], v[124:125], v[156:157]
	v_pk_add_f32 v[126:127], v[126:127], v[154:155]
	v_pk_fma_f32 v[228:229], v[172:173], v[228:229], v[180:181]
	v_cvt_pk_f16_f32 v98, v126, v127
	v_cvt_pk_f16_f32 v154, v124, v125
	v_cvt_pk_f16_f32 v155, v130, v131
	s_waitcnt vmcnt(3)
	v_cvt_f32_f16_sdwa v131, v222 dst_sel:DWORD dst_unused:UNUSED_PAD src0_sel:WORD_1
	v_cvt_f32_f16_e32 v130, v222
	v_cvt_f32_f16_sdwa v127, v224 dst_sel:DWORD dst_unused:UNUSED_PAD src0_sel:WORD_1
	v_cvt_f32_f16_e32 v126, v224
	v_cvt_f32_f16_sdwa v125, v225 dst_sel:DWORD dst_unused:UNUSED_PAD src0_sel:WORD_1
	v_cvt_f32_f16_e32 v124, v225
	v_pk_add_f32 v[128:129], v[128:129], v[228:229]
	v_sub_f32_e32 v126, v126, v210
	v_cvt_pk_f16_f32 v156, v128, v129
	v_cvt_f32_f16_sdwa v129, v223 dst_sel:DWORD dst_unused:UNUSED_PAD src0_sel:WORD_1
	v_cvt_f32_f16_e32 v128, v223
	v_sub_f32_e32 v124, v124, v210
	v_sub_f32_e32 v125, v125, v210
	v_sub_f32_e32 v127, v127, v210
	v_sub_f32_e32 v130, v130, v210
	v_sub_f32_e32 v131, v131, v210
	v_pk_mul_f32 v[130:131], v[210:211], v[130:131] op_sel:[1,0]
	v_pk_mul_f32 v[126:127], v[210:211], v[126:127] op_sel:[1,0]
	v_pk_mul_f32 v[124:125], v[210:211], v[124:125] op_sel:[1,0]
	v_sub_f32_e32 v128, v128, v210
	v_sub_f32_e32 v129, v129, v210
	v_pk_fma_f32 v[124:125], v[196:197], v[124:125], v[202:203]
	v_pk_fma_f32 v[126:127], v[190:191], v[126:127], v[198:199]
	v_pk_fma_f32 v[130:131], v[176:177], v[130:131], v[182:183]
	v_pk_mul_f32 v[128:129], v[210:211], v[128:129] op_sel:[1,0]
	v_pk_add_f32 v[120:121], v[120:121], v[130:131]
	v_pk_add_f32 v[116:117], v[116:117], v[126:127]
	v_pk_add_f32 v[118:119], v[118:119], v[124:125]
	v_pk_fma_f32 v[128:129], v[178:179], v[128:129], v[186:187]
	v_cvt_pk_f16_f32 v124, v118, v119
	v_cvt_pk_f16_f32 v119, v116, v117
	v_cvt_pk_f16_f32 v117, v120, v121
	v_pk_add_f32 v[122:123], v[122:123], v[128:129]
	v_cndmask_b32_e64 v116, v156, v117, s[72:73]
	v_cvt_pk_f16_f32 v118, v122, v123
	s_nop 0
	v_mov_b32_dpp v120, v116 row_ror:8 row_mask:0xf bank_mask:0xf bound_ctrl:1
	v_cndmask_b32_e64 v116, v120, v156, s[72:73]
	v_cndmask_b32_e64 v120, v117, v120, s[72:73]
	v_cndmask_b32_e64 v117, v155, v118, s[72:73]
	s_nop 1
	v_mov_b32_dpp v121, v117 row_ror:8 row_mask:0xf bank_mask:0xf bound_ctrl:1
	v_cndmask_b32_e64 v117, v121, v155, s[72:73]
	v_cndmask_b32_e64 v121, v118, v121, s[72:73]
	v_cndmask_b32_e64 v118, v154, v119, s[72:73]
	s_nop 1
	v_mov_b32_dpp v122, v118 row_ror:8 row_mask:0xf bank_mask:0xf bound_ctrl:1
	v_cndmask_b32_e64 v118, v122, v154, s[72:73]
	v_cndmask_b32_e64 v122, v119, v122, s[72:73]
	v_cndmask_b32_e64 v119, v98, v124, s[72:73]
	s_nop 1
	v_mov_b32_dpp v123, v119 row_ror:8 row_mask:0xf bank_mask:0xf bound_ctrl:1
	v_cndmask_b32_e64 v119, v123, v98, s[72:73]
	global_store_dwordx4 v[164:165], v[116:119], off
	v_cndmask_b32_e64 v123, v124, v123, s[72:73]
	s_waitcnt vmcnt(2)
;     __device__ __forceinline__ void operator()(Acc& acc, const Unit& u, int wr, int wc, int fr, int fq) const {
;     ...
;             for (int ai = 0; ai < 2; ++ai)
; #pragma unroll
;               for (int mp = 0; mp < 4; mp += 2) {
;                 f32x2 ms[2]; h16x8 rr[2][2];
; #pragma unroll
;                 for (int m = 0; m < 2; ++m) { const int row = row0 + ai * HALF + (mp + m) * 16; ms[m] = st[row];
; #pragma unroll
;                     for (int bj = 0; bj < 2; ++bj) rr[m][bj] = *(const h16x8*)(pre + (size_t)row * DM + colb + bj * BJ); }
;                 asm volatile("" ::: "memory");
; #pragma unroll
;                 for (int m = 0; m < 2; ++m) { u32x4 dd[2];
; #pragma unroll
;                     for (int bj = 0; bj < 2; ++bj) { const f32x8 r = __builtin_convertvector(rr[m][bj], f32x8);
;                         const f32x4 r0 = {r[0], r[1], r[2], r[3]}, r1 = {r[4], r[5], r[6], r[7]};
;                         const f32x4 o0 = ((r0 - ms[m].x) * ms[m].y) * gv[bj][0] + bv[bj][0] + acc[ai][bj][mp + m][0], o1 = ((r1 - ms[m].x) * ms[m].y) * gv[bj][1] + bv[bj][1] + acc[ai][bj][mp + m][1];
;                         const f32x8 o = {o0[0], o0[1], o0[2], o0[3], o1[0], o1[1], o1[2], o1[3]};
;                         dd[bj] = __builtin_bit_cast(u32x4, __builtin_convertvector(o, h16x8)); }
;                     store_pair128(pre + sbase + (size_t)(ai * HALF + (mp + m) * 16) * DM, (size_t)8 * DM, dd[0], dd[1], lo); }
;                 asm volatile("" ::: "memory"); }
	v_cvt_f32_f16_sdwa v98, v136 dst_sel:DWORD dst_unused:UNUSED_PAD src0_sel:WORD_1
	v_add_co_u32_e32 v116, vcc, s2, v164
	v_cvt_f32_f16_sdwa v119, v138 dst_sel:DWORD dst_unused:UNUSED_PAD src0_sel:WORD_1
	s_nop 0
	v_addc_co_u32_e32 v117, vcc, 0, v165, vcc
	global_store_dwordx4 v[116:117], v[120:123], off
	v_cvt_f32_f16_e32 v118, v138
	v_cvt_f32_f16_sdwa v117, v139 dst_sel:DWORD dst_unused:UNUSED_PAD src0_sel:WORD_1
	v_cvt_f32_f16_sdwa v121, v137 dst_sel:DWORD dst_unused:UNUSED_PAD src0_sel:WORD_1
	v_cvt_f32_f16_e32 v120, v137
	v_cvt_f32_f16_e32 v116, v139
	v_cvt_f32_f16_e32 v122, v136
	v_sub_f32_e32 v117, v117, v208
	v_sub_f32_e32 v118, v118, v208
	v_sub_f32_e32 v116, v116, v208
	v_sub_f32_e32 v119, v119, v208
	v_sub_f32_e32 v120, v120, v208
	v_sub_f32_e32 v121, v121, v208
	v_pk_mul_f32 v[120:121], v[208:209], v[120:121] op_sel:[1,0]
	v_pk_mul_f32 v[118:119], v[208:209], v[118:119] op_sel:[1,0]
	v_pk_mul_f32 v[116:117], v[208:209], v[116:117] op_sel:[1,0]
	v_sub_f32_e32 v122, v122, v208
	v_sub_f32_e32 v123, v98, v208
	v_pk_fma_f32 v[116:117], v[192:193], v[116:117], v[200:201]
	v_pk_fma_f32 v[118:119], v[188:189], v[118:119], v[194:195]
	v_pk_fma_f32 v[120:121], v[174:175], v[120:121], v[184:185]
	v_pk_mul_f32 v[122:123], v[208:209], v[122:123] op_sel:[1,0]
	v_pk_add_f32 v[114:115], v[114:115], v[120:121]
	v_pk_add_f32 v[108:109], v[108:109], v[118:119]
	v_pk_add_f32 v[110:111], v[110:111], v[116:117]
	v_pk_fma_f32 v[122:123], v[172:173], v[122:123], v[180:181]
	v_cvt_pk_f16_f32 v98, v110, v111
	v_cvt_pk_f16_f32 v116, v108, v109
	v_cvt_pk_f16_f32 v117, v114, v115
	s_waitcnt vmcnt(2)
	v_cvt_f32_f16_sdwa v115, v132 dst_sel:DWORD dst_unused:UNUSED_PAD src0_sel:WORD_1
	v_cvt_f32_f16_e32 v114, v132
	v_cvt_f32_f16_sdwa v111, v134 dst_sel:DWORD dst_unused:UNUSED_PAD src0_sel:WORD_1
	v_cvt_f32_f16_e32 v110, v134
	v_cvt_f32_f16_sdwa v109, v135 dst_sel:DWORD dst_unused:UNUSED_PAD src0_sel:WORD_1
	v_cvt_f32_f16_e32 v108, v135
	v_pk_add_f32 v[112:113], v[112:113], v[122:123]
	v_sub_f32_e32 v110, v110, v208
	v_cvt_pk_f16_f32 v118, v112, v113
	v_cvt_f32_f16_sdwa v113, v133 dst_sel:DWORD dst_unused:UNUSED_PAD src0_sel:WORD_1
	v_cvt_f32_f16_e32 v112, v133
	v_sub_f32_e32 v108, v108, v208
	v_sub_f32_e32 v109, v109, v208
	v_sub_f32_e32 v111, v111, v208
	v_sub_f32_e32 v114, v114, v208
	v_sub_f32_e32 v115, v115, v208
	v_pk_mul_f32 v[114:115], v[208:209], v[114:115] op_sel:[1,0]
	v_pk_mul_f32 v[110:111], v[208:209], v[110:111] op_sel:[1,0]
	v_pk_mul_f32 v[108:109], v[208:209], v[108:109] op_sel:[1,0]
	v_sub_f32_e32 v112, v112, v208
	v_sub_f32_e32 v113, v113, v208
	v_pk_fma_f32 v[108:109], v[196:197], v[108:109], v[202:203]
	v_pk_fma_f32 v[110:111], v[190:191], v[110:111], v[198:199]
	v_pk_fma_f32 v[114:115], v[176:177], v[114:115], v[182:183]
	v_pk_mul_f32 v[112:113], v[208:209], v[112:113] op_sel:[1,0]
	v_pk_add_f32 v[104:105], v[104:105], v[114:115]
	v_pk_add_f32 v[100:101], v[100:101], v[110:111]
	v_pk_add_f32 v[102:103], v[102:103], v[108:109]
	v_pk_fma_f32 v[112:113], v[178:179], v[112:113], v[186:187]
	v_cvt_pk_f16_f32 v108, v102, v103
	v_cvt_pk_f16_f32 v103, v100, v101
	v_cvt_pk_f16_f32 v101, v104, v105
	v_pk_add_f32 v[106:107], v[106:107], v[112:113]
	v_cndmask_b32_e64 v100, v118, v101, s[72:73]
	v_cvt_pk_f16_f32 v102, v106, v107
	s_mov_b32 s2, 0x10000
	v_mov_b32_dpp v104, v100 row_ror:8 row_mask:0xf bank_mask:0xf bound_ctrl:1
	v_cndmask_b32_e64 v100, v104, v118, s[72:73]
	v_cndmask_b32_e64 v104, v101, v104, s[72:73]
	v_cndmask_b32_e64 v101, v117, v102, s[72:73]
	s_nop 1
	v_mov_b32_dpp v105, v101 row_ror:8 row_mask:0xf bank_mask:0xf bound_ctrl:1
	v_cndmask_b32_e64 v101, v105, v117, s[72:73]
	v_cndmask_b32_e64 v105, v102, v105, s[72:73]
	v_cndmask_b32_e64 v102, v116, v103, s[72:73]
	s_nop 1
	v_mov_b32_dpp v106, v102 row_ror:8 row_mask:0xf bank_mask:0xf bound_ctrl:1
	v_cndmask_b32_e64 v102, v106, v116, s[72:73]
	v_cndmask_b32_e64 v106, v103, v106, s[72:73]
	v_cndmask_b32_e64 v103, v98, v108, s[72:73]
	s_nop 1
	v_mov_b32_dpp v107, v103 row_ror:8 row_mask:0xf bank_mask:0xf bound_ctrl:1
	v_cndmask_b32_e64 v103, v107, v98, s[72:73]
	v_cndmask_b32_e64 v107, v108, v107, s[72:73]
	v_add_co_u32_e32 v108, vcc, s2, v164
	s_mov_b32 s2, 0x18000
	s_nop 0
	v_addc_co_u32_e32 v109, vcc, 0, v165, vcc
	global_store_dwordx4 v[108:109], v[100:103], off
	s_nop 1
	v_add_co_u32_e32 v100, vcc, s2, v164
	s_mov_b32 s2, 0x38000
	s_nop 0
	v_addc_co_u32_e32 v101, vcc, 0, v165, vcc
	global_store_dwordx4 v[100:101], v[104:107], off
	v_lshl_add_u64 v[100:101], v[168:169], 3, s[66:67]
	global_load_dwordx2 v[118:119], v[100:101], off
	v_lshlrev_b64 v[100:101], 12, v[168:169]
	v_lshl_add_u64 v[100:101], v[206:207], 0, v[100:101]
	global_load_dwordx4 v[106:109], v[100:101], off
	global_load_dwordx4 v[110:113], v[100:101], off offset:64
	v_lshl_add_u64 v[100:101], v[166:167], 3, s[66:67]
	global_load_dwordx2 v[104:105], v[100:101], off
	v_lshlrev_b64 v[100:101], 12, v[166:167]
	v_lshl_add_u64 v[100:101], v[206:207], 0, v[100:101]
	global_load_dwordx4 v[114:117], v[100:101], off
	s_nop 0
	global_load_dwordx4 v[100:103], v[100:101], off offset:64
	s_waitcnt vmcnt(4)
;     __device__ __forceinline__ void operator()(Acc& acc, const Unit& u, int wr, int wc, int fr, int fq) const {
;     ...
;             for (int ai = 0; ai < 2; ++ai)
; #pragma unroll
;               for (int mp = 0; mp < 4; mp += 2) {
;                 f32x2 ms[2]; h16x8 rr[2][2];
; #pragma unroll
;                 for (int m = 0; m < 2; ++m) { const int row = row0 + ai * HALF + (mp + m) * 16; ms[m] = st[row];
; #pragma unroll
;                     for (int bj = 0; bj < 2; ++bj) rr[m][bj] = *(const h16x8*)(pre + (size_t)row * DM + colb + bj * BJ); }
;                 asm volatile("" ::: "memory");
; #pragma unroll
;                 for (int m = 0; m < 2; ++m) { u32x4 dd[2];
; #pragma unroll
;                     for (int bj = 0; bj < 2; ++bj) { const f32x8 r = __builtin_convertvector(rr[m][bj], f32x8);
;                         const f32x4 r0 = {r[0], r[1], r[2], r[3]}, r1 = {r[4], r[5], r[6], r[7]};
;                         const f32x4 o0 = ((r0 - ms[m].x) * ms[m].y) * gv[bj][0] + bv[bj][0] + acc[ai][bj][mp + m][0], o1 = ((r1 - ms[m].x) * ms[m].y) * gv[bj][1] + bv[bj][1] + acc[ai][bj][mp + m][1];
;                         const f32x8 o = {o0[0], o0[1], o0[2], o0[3], o1[0], o1[1], o1[2], o1[3]};
;                         dd[bj] = __builtin_bit_cast(u32x4, __builtin_convertvector(o, h16x8)); }
;                     store_pair128(pre + sbase + (size_t)(ai * HALF + (mp + m) * 16) * DM, (size_t)8 * DM, dd[0], dd[1], lo); }
;                 asm volatile("" ::: "memory"); }
	v_cvt_f32_f16_sdwa v98, v106 dst_sel:DWORD dst_unused:UNUSED_PAD src0_sel:WORD_1
	v_cvt_f32_f16_e32 v122, v106
	v_cvt_f32_f16_sdwa v121, v107 dst_sel:DWORD dst_unused:UNUSED_PAD src0_sel:WORD_1
	v_cvt_f32_f16_e32 v120, v107
	v_cvt_f32_f16_sdwa v123, v108 dst_sel:DWORD dst_unused:UNUSED_PAD src0_sel:WORD_1
	v_cvt_f32_f16_e32 v108, v108
	v_cvt_f32_f16_sdwa v107, v109 dst_sel:DWORD dst_unused:UNUSED_PAD src0_sel:WORD_1
	v_cvt_f32_f16_e32 v106, v109
	v_sub_f32_e32 v109, v123, v118
	v_sub_f32_e32 v108, v108, v118
	v_sub_f32_e32 v107, v107, v118
	v_sub_f32_e32 v106, v106, v118
	v_sub_f32_e32 v120, v120, v118
	v_sub_f32_e32 v121, v121, v118
	v_pk_mul_f32 v[120:121], v[118:119], v[120:121] op_sel:[1,0]
	v_pk_mul_f32 v[108:109], v[118:119], v[108:109] op_sel:[1,0]
	v_pk_mul_f32 v[106:107], v[118:119], v[106:107] op_sel:[1,0]
	v_sub_f32_e32 v122, v122, v118
	v_sub_f32_e32 v123, v98, v118
	v_pk_fma_f32 v[106:107], v[192:193], v[106:107], v[200:201]
	v_pk_fma_f32 v[108:109], v[188:189], v[108:109], v[194:195]
	v_pk_fma_f32 v[120:121], v[174:175], v[120:121], v[184:185]
	v_pk_mul_f32 v[122:123], v[118:119], v[122:123] op_sel:[1,0]
	v_pk_add_f32 v[96:97], v[96:97], v[120:121]
	v_pk_add_f32 v[90:91], v[90:91], v[108:109]
	v_pk_add_f32 v[92:93], v[92:93], v[106:107]
	v_pk_fma_f32 v[122:123], v[172:173], v[122:123], v[180:181]
	v_cvt_pk_f16_f32 v98, v92, v93
	v_cvt_pk_f16_f32 v106, v90, v91
	v_cvt_pk_f16_f32 v107, v96, v97
	s_waitcnt vmcnt(3)
	v_cvt_f32_f16_sdwa v97, v110 dst_sel:DWORD dst_unused:UNUSED_PAD src0_sel:WORD_1
	v_cvt_f32_f16_e32 v96, v110
	v_cvt_f32_f16_sdwa v93, v112 dst_sel:DWORD dst_unused:UNUSED_PAD src0_sel:WORD_1
	v_cvt_f32_f16_e32 v92, v112
	v_cvt_f32_f16_sdwa v91, v113 dst_sel:DWORD dst_unused:UNUSED_PAD src0_sel:WORD_1
	v_cvt_f32_f16_e32 v90, v113
	v_pk_add_f32 v[94:95], v[94:95], v[122:123]
	v_sub_f32_e32 v92, v92, v118
	v_cvt_pk_f16_f32 v108, v94, v95
	v_cvt_f32_f16_sdwa v95, v111 dst_sel:DWORD dst_unused:UNUSED_PAD src0_sel:WORD_1
	v_cvt_f32_f16_e32 v94, v111
	v_sub_f32_e32 v90, v90, v118
	v_sub_f32_e32 v91, v91, v118
	v_sub_f32_e32 v93, v93, v118
	v_sub_f32_e32 v96, v96, v118
	v_sub_f32_e32 v97, v97, v118
	v_pk_mul_f32 v[96:97], v[118:119], v[96:97] op_sel:[1,0]
	v_pk_mul_f32 v[92:93], v[118:119], v[92:93] op_sel:[1,0]
	v_pk_mul_f32 v[90:91], v[118:119], v[90:91] op_sel:[1,0]
	v_sub_f32_e32 v94, v94, v118
	v_sub_f32_e32 v95, v95, v118
	v_pk_fma_f32 v[90:91], v[196:197], v[90:91], v[202:203]
	v_pk_fma_f32 v[92:93], v[190:191], v[92:93], v[198:199]
	v_pk_fma_f32 v[96:97], v[176:177], v[96:97], v[182:183]
	v_pk_mul_f32 v[94:95], v[118:119], v[94:95] op_sel:[1,0]
	v_pk_add_f32 v[86:87], v[86:87], v[96:97]
	v_pk_add_f32 v[82:83], v[82:83], v[92:93]
	v_pk_add_f32 v[84:85], v[84:85], v[90:91]
	v_pk_fma_f32 v[94:95], v[178:179], v[94:95], v[186:187]
	v_cvt_pk_f16_f32 v90, v84, v85
	v_cvt_pk_f16_f32 v85, v82, v83
	v_cvt_pk_f16_f32 v83, v86, v87
	v_pk_add_f32 v[88:89], v[88:89], v[94:95]
	v_cndmask_b32_e64 v82, v108, v83, s[72:73]
	v_cvt_pk_f16_f32 v84, v88, v89
	s_nop 0
	v_mov_b32_dpp v86, v82 row_ror:8 row_mask:0xf bank_mask:0xf bound_ctrl:1
	v_cndmask_b32_e64 v82, v86, v108, s[72:73]
	v_cndmask_b32_e64 v86, v83, v86, s[72:73]
	v_cndmask_b32_e64 v83, v107, v84, s[72:73]
	s_nop 1
	v_mov_b32_dpp v87, v83 row_ror:8 row_mask:0xf bank_mask:0xf bound_ctrl:1
	v_cndmask_b32_e64 v83, v87, v107, s[72:73]
	v_cndmask_b32_e64 v87, v84, v87, s[72:73]
	v_cndmask_b32_e64 v84, v106, v85, s[72:73]
	s_nop 1
	v_mov_b32_dpp v88, v84 row_ror:8 row_mask:0xf bank_mask:0xf bound_ctrl:1
	v_cndmask_b32_e64 v84, v88, v106, s[72:73]
	v_cndmask_b32_e64 v88, v85, v88, s[72:73]
	v_cndmask_b32_e64 v85, v98, v90, s[72:73]
	s_nop 1
	v_mov_b32_dpp v89, v85 row_ror:8 row_mask:0xf bank_mask:0xf bound_ctrl:1
	v_cndmask_b32_e64 v85, v89, v98, s[72:73]
	v_cndmask_b32_e64 v89, v90, v89, s[72:73]
	v_add_co_u32_e32 v90, vcc, s85, v164
	s_nop 1
	v_addc_co_u32_e32 v91, vcc, 0, v165, vcc
	global_store_dwordx4 v[90:91], v[82:85], off
	s_nop 1
	v_add_co_u32_e32 v82, vcc, s86, v164
	s_waitcnt vmcnt(2)
	v_cvt_f32_f16_sdwa v85, v116 dst_sel:DWORD dst_unused:UNUSED_PAD src0_sel:WORD_1
	v_addc_co_u32_e32 v83, vcc, 0, v165, vcc
	global_store_dwordx4 v[82:83], v[86:89], off
	v_cvt_f32_f16_e32 v84, v116
	v_cvt_f32_f16_sdwa v83, v117 dst_sel:DWORD dst_unused:UNUSED_PAD src0_sel:WORD_1
	v_cvt_f32_f16_sdwa v87, v115 dst_sel:DWORD dst_unused:UNUSED_PAD src0_sel:WORD_1
	v_cvt_f32_f16_e32 v86, v115
	v_cvt_f32_f16_e32 v82, v117
	v_cvt_f32_f16_sdwa v89, v114 dst_sel:DWORD dst_unused:UNUSED_PAD src0_sel:WORD_1
	v_cvt_f32_f16_e32 v88, v114
	v_sub_f32_e32 v83, v83, v104
	v_sub_f32_e32 v82, v82, v104
	v_sub_f32_e32 v84, v84, v104
	v_sub_f32_e32 v85, v85, v104
	v_sub_f32_e32 v86, v86, v104
	v_sub_f32_e32 v87, v87, v104
	v_pk_mul_f32 v[86:87], v[104:105], v[86:87] op_sel:[1,0]
	v_pk_mul_f32 v[84:85], v[104:105], v[84:85] op_sel:[1,0]
	v_pk_mul_f32 v[82:83], v[104:105], v[82:83] op_sel:[1,0]
	v_sub_f32_e32 v88, v88, v104
	v_sub_f32_e32 v89, v89, v104
	v_pk_fma_f32 v[82:83], v[192:193], v[82:83], v[200:201]
	v_pk_fma_f32 v[84:85], v[188:189], v[84:85], v[194:195]
	v_pk_fma_f32 v[86:87], v[174:175], v[86:87], v[184:185]
	v_pk_mul_f32 v[88:89], v[104:105], v[88:89] op_sel:[1,0]
	v_pk_add_f32 v[80:81], v[80:81], v[86:87]
	v_pk_add_f32 v[74:75], v[74:75], v[84:85]
	v_pk_add_f32 v[76:77], v[76:77], v[82:83]
	v_pk_fma_f32 v[88:89], v[172:173], v[88:89], v[180:181]
	v_cvt_pk_f16_f32 v82, v76, v77
	v_cvt_pk_f16_f32 v83, v74, v75
	v_cvt_pk_f16_f32 v84, v80, v81
	s_waitcnt vmcnt(2)
;     __device__ __forceinline__ void operator()(Acc& acc, const Unit& u, int wr, int wc, int fr, int fq) const {
;     ...
;             for (int ai = 0; ai < 2; ++ai)
; #pragma unroll
;               for (int mp = 0; mp < 4; mp += 2) {
;                 f32x2 ms[2]; h16x8 rr[2][2];
; #pragma unroll
;                 for (int m = 0; m < 2; ++m) { const int row = row0 + ai * HALF + (mp + m) * 16; ms[m] = st[row];
; #pragma unroll
;                     for (int bj = 0; bj < 2; ++bj) rr[m][bj] = *(const h16x8*)(pre + (size_t)row * DM + colb + bj * BJ); }
;                 asm volatile("" ::: "memory");
; #pragma unroll
;                 for (int m = 0; m < 2; ++m) { u32x4 dd[2];
; #pragma unroll
;                     for (int bj = 0; bj < 2; ++bj) { const f32x8 r = __builtin_convertvector(rr[m][bj], f32x8);
;                         const f32x4 r0 = {r[0], r[1], r[2], r[3]}, r1 = {r[4], r[5], r[6], r[7]};
;                         const f32x4 o0 = ((r0 - ms[m].x) * ms[m].y) * gv[bj][0] + bv[bj][0] + acc[ai][bj][mp + m][0], o1 = ((r1 - ms[m].x) * ms[m].y) * gv[bj][1] + bv[bj][1] + acc[ai][bj][mp + m][1];
;                         const f32x8 o = {o0[0], o0[1], o0[2], o0[3], o1[0], o1[1], o1[2], o1[3]};
;                         dd[bj] = __builtin_bit_cast(u32x4, __builtin_convertvector(o, h16x8)); }
;                     store_pair128(pre + sbase + (size_t)(ai * HALF + (mp + m) * 16) * DM, (size_t)8 * DM, dd[0], dd[1], lo); }
;                 asm volatile("" ::: "memory"); }
	v_cvt_f32_f16_sdwa v81, v100 dst_sel:DWORD dst_unused:UNUSED_PAD src0_sel:WORD_1
	v_cvt_f32_f16_e32 v80, v100
	v_cvt_f32_f16_sdwa v77, v102 dst_sel:DWORD dst_unused:UNUSED_PAD src0_sel:WORD_1
	v_cvt_f32_f16_e32 v76, v102
	v_cvt_f32_f16_sdwa v75, v103 dst_sel:DWORD dst_unused:UNUSED_PAD src0_sel:WORD_1
	v_cvt_f32_f16_e32 v74, v103
	v_pk_add_f32 v[78:79], v[78:79], v[88:89]
	v_sub_f32_e32 v76, v76, v104
	v_cvt_pk_f16_f32 v85, v78, v79
	v_cvt_f32_f16_sdwa v79, v101 dst_sel:DWORD dst_unused:UNUSED_PAD src0_sel:WORD_1
	v_cvt_f32_f16_e32 v78, v101
	v_sub_f32_e32 v74, v74, v104
	v_sub_f32_e32 v75, v75, v104
	v_sub_f32_e32 v77, v77, v104
	v_sub_f32_e32 v80, v80, v104
	v_sub_f32_e32 v81, v81, v104
	v_pk_mul_f32 v[80:81], v[104:105], v[80:81] op_sel:[1,0]
	v_pk_mul_f32 v[76:77], v[104:105], v[76:77] op_sel:[1,0]
	v_pk_mul_f32 v[74:75], v[104:105], v[74:75] op_sel:[1,0]
	v_sub_f32_e32 v78, v78, v104
	v_sub_f32_e32 v79, v79, v104
	v_pk_fma_f32 v[74:75], v[196:197], v[74:75], v[202:203]
	v_pk_fma_f32 v[76:77], v[190:191], v[76:77], v[198:199]
	v_pk_fma_f32 v[80:81], v[176:177], v[80:81], v[182:183]
	v_pk_mul_f32 v[78:79], v[104:105], v[78:79] op_sel:[1,0]
	v_pk_add_f32 v[70:71], v[70:71], v[80:81]
	v_pk_add_f32 v[66:67], v[66:67], v[76:77]
	v_pk_add_f32 v[68:69], v[68:69], v[74:75]
	v_pk_fma_f32 v[78:79], v[178:179], v[78:79], v[186:187]
	v_cvt_pk_f16_f32 v74, v68, v69
	v_cvt_pk_f16_f32 v69, v66, v67
	v_cvt_pk_f16_f32 v67, v70, v71
	v_pk_add_f32 v[72:73], v[72:73], v[78:79]
	v_cndmask_b32_e64 v66, v85, v67, s[72:73]
	v_cvt_pk_f16_f32 v68, v72, v73
	s_nop 0
	v_mov_b32_dpp v70, v66 row_ror:8 row_mask:0xf bank_mask:0xf bound_ctrl:1
	v_cndmask_b32_e64 v66, v70, v85, s[72:73]
	v_cndmask_b32_e64 v70, v67, v70, s[72:73]
	v_cndmask_b32_e64 v67, v84, v68, s[72:73]
	s_nop 1
	v_mov_b32_dpp v71, v67 row_ror:8 row_mask:0xf bank_mask:0xf bound_ctrl:1
	v_cndmask_b32_e64 v67, v71, v84, s[72:73]
	v_cndmask_b32_e64 v71, v68, v71, s[72:73]
	v_cndmask_b32_e64 v68, v83, v69, s[72:73]
	s_nop 1
	v_mov_b32_dpp v72, v68 row_ror:8 row_mask:0xf bank_mask:0xf bound_ctrl:1
	v_cndmask_b32_e64 v68, v72, v83, s[72:73]
	v_cndmask_b32_e64 v72, v69, v72, s[72:73]
	v_cndmask_b32_e64 v69, v82, v74, s[72:73]
	s_nop 1
	v_mov_b32_dpp v73, v69 row_ror:8 row_mask:0xf bank_mask:0xf bound_ctrl:1
	v_cndmask_b32_e64 v69, v73, v82, s[72:73]
	v_cndmask_b32_e64 v73, v74, v73, s[72:73]
	v_add_co_u32_e32 v74, vcc, s87, v164
	s_nop 1
	v_addc_co_u32_e32 v75, vcc, 0, v165, vcc
	global_store_dwordx4 v[74:75], v[66:69], off
	s_nop 1
	v_add_co_u32_e32 v66, vcc, s2, v164
	s_mov_b64 s[2:3], 0x80000
	s_nop 0
	v_addc_co_u32_e32 v67, vcc, 0, v165, vcc
	global_store_dwordx4 v[66:67], v[70:73], off
	v_lshl_add_u64 v[66:67], v[204:205], 0, s[2:3]
	s_mov_b32 s2, 0x80000
	v_add_co_u32_e32 v68, vcc, s2, v204
	global_load_dwordx2 v[84:85], v[170:171], off offset:1024
	s_nop 0
	v_addc_co_u32_e32 v69, vcc, 0, v205, vcc
	global_load_dwordx4 v[72:75], v[68:69], off
	global_load_dwordx4 v[76:79], v[66:67], off offset:64
	global_load_dwordx2 v[70:71], v[170:171], off offset:1152
	v_add_co_u32_e32 v68, vcc, s82, v204
	v_lshl_add_u64 v[66:67], v[204:205], 0, s[70:71]
	s_nop 0
	v_addc_co_u32_e32 v69, vcc, 0, v205, vcc
	global_load_dwordx4 v[80:83], v[68:69], off
	s_nop 0
	global_load_dwordx4 v[66:69], v[66:67], off offset:64
	s_waitcnt vmcnt(4)
	v_cvt_f32_f16_sdwa v89, v72 dst_sel:DWORD dst_unused:UNUSED_PAD src0_sel:WORD_1
	v_cvt_f32_f16_e32 v88, v72
	v_cvt_f32_f16_sdwa v87, v73 dst_sel:DWORD dst_unused:UNUSED_PAD src0_sel:WORD_1
	v_cvt_f32_f16_e32 v86, v73
	v_cvt_f32_f16_sdwa v90, v74 dst_sel:DWORD dst_unused:UNUSED_PAD src0_sel:WORD_1
	v_cvt_f32_f16_e32 v74, v74
	v_cvt_f32_f16_sdwa v73, v75 dst_sel:DWORD dst_unused:UNUSED_PAD src0_sel:WORD_1
	v_cvt_f32_f16_e32 v72, v75
	v_sub_f32_e32 v75, v90, v84
	v_sub_f32_e32 v74, v74, v84
	v_sub_f32_e32 v73, v73, v84
	v_sub_f32_e32 v72, v72, v84
	v_sub_f32_e32 v86, v86, v84
	v_sub_f32_e32 v87, v87, v84
	v_pk_mul_f32 v[86:87], v[84:85], v[86:87] op_sel:[1,0]
	v_pk_mul_f32 v[74:75], v[84:85], v[74:75] op_sel:[1,0]
	v_pk_mul_f32 v[72:73], v[84:85], v[72:73] op_sel:[1,0]
	v_sub_f32_e32 v88, v88, v84
	v_sub_f32_e32 v89, v89, v84
	v_pk_fma_f32 v[72:73], v[192:193], v[72:73], v[200:201]
	v_pk_fma_f32 v[74:75], v[188:189], v[74:75], v[194:195]
	v_pk_fma_f32 v[86:87], v[174:175], v[86:87], v[184:185]
	v_pk_mul_f32 v[88:89], v[84:85], v[88:89] op_sel:[1,0]
	v_pk_add_f32 v[64:65], v[64:65], v[86:87]
	v_pk_add_f32 v[58:59], v[58:59], v[74:75]
	v_pk_add_f32 v[60:61], v[60:61], v[72:73]
	v_pk_fma_f32 v[88:89], v[172:173], v[88:89], v[180:181]
	v_cvt_pk_f16_f32 v72, v60, v61
	v_cvt_pk_f16_f32 v73, v58, v59
	v_cvt_pk_f16_f32 v74, v64, v65
	s_waitcnt vmcnt(3)
;     __device__ __forceinline__ void operator()(Acc& acc, const Unit& u, int wr, int wc, int fr, int fq) const {
;     ...
;             for (int ai = 0; ai < 2; ++ai)
; #pragma unroll
;               for (int mp = 0; mp < 4; mp += 2) {
;                 f32x2 ms[2]; h16x8 rr[2][2];
; #pragma unroll
;                 for (int m = 0; m < 2; ++m) { const int row = row0 + ai * HALF + (mp + m) * 16; ms[m] = st[row];
; #pragma unroll
;                     for (int bj = 0; bj < 2; ++bj) rr[m][bj] = *(const h16x8*)(pre + (size_t)row * DM + colb + bj * BJ); }
;                 asm volatile("" ::: "memory");
; #pragma unroll
;                 for (int m = 0; m < 2; ++m) { u32x4 dd[2];
; #pragma unroll
;                     for (int bj = 0; bj < 2; ++bj) { const f32x8 r = __builtin_convertvector(rr[m][bj], f32x8);
;                         const f32x4 r0 = {r[0], r[1], r[2], r[3]}, r1 = {r[4], r[5], r[6], r[7]};
;                         const f32x4 o0 = ((r0 - ms[m].x) * ms[m].y) * gv[bj][0] + bv[bj][0] + acc[ai][bj][mp + m][0], o1 = ((r1 - ms[m].x) * ms[m].y) * gv[bj][1] + bv[bj][1] + acc[ai][bj][mp + m][1];
;                         const f32x8 o = {o0[0], o0[1], o0[2], o0[3], o1[0], o1[1], o1[2], o1[3]};
;                         dd[bj] = __builtin_bit_cast(u32x4, __builtin_convertvector(o, h16x8)); }
;                     store_pair128(pre + sbase + (size_t)(ai * HALF + (mp + m) * 16) * DM, (size_t)8 * DM, dd[0], dd[1], lo); }
;                 asm volatile("" ::: "memory"); }
	v_cvt_f32_f16_sdwa v65, v76 dst_sel:DWORD dst_unused:UNUSED_PAD src0_sel:WORD_1
	v_cvt_f32_f16_e32 v64, v76
	v_cvt_f32_f16_sdwa v61, v78 dst_sel:DWORD dst_unused:UNUSED_PAD src0_sel:WORD_1
	v_cvt_f32_f16_e32 v60, v78
	v_cvt_f32_f16_sdwa v59, v79 dst_sel:DWORD dst_unused:UNUSED_PAD src0_sel:WORD_1
	v_cvt_f32_f16_e32 v58, v79
	v_pk_add_f32 v[62:63], v[62:63], v[88:89]
	v_sub_f32_e32 v60, v60, v84
	v_cvt_pk_f16_f32 v75, v62, v63
	v_cvt_f32_f16_sdwa v63, v77 dst_sel:DWORD dst_unused:UNUSED_PAD src0_sel:WORD_1
	v_cvt_f32_f16_e32 v62, v77
	v_sub_f32_e32 v58, v58, v84
	v_sub_f32_e32 v59, v59, v84
	v_sub_f32_e32 v61, v61, v84
	v_sub_f32_e32 v64, v64, v84
	v_sub_f32_e32 v65, v65, v84
	v_pk_mul_f32 v[64:65], v[84:85], v[64:65] op_sel:[1,0]
	v_pk_mul_f32 v[60:61], v[84:85], v[60:61] op_sel:[1,0]
	v_pk_mul_f32 v[58:59], v[84:85], v[58:59] op_sel:[1,0]
	v_sub_f32_e32 v62, v62, v84
	v_sub_f32_e32 v63, v63, v84
	v_pk_fma_f32 v[58:59], v[196:197], v[58:59], v[202:203]
	v_pk_fma_f32 v[60:61], v[190:191], v[60:61], v[198:199]
	v_pk_fma_f32 v[64:65], v[176:177], v[64:65], v[182:183]
	v_pk_mul_f32 v[62:63], v[84:85], v[62:63] op_sel:[1,0]
	v_pk_add_f32 v[54:55], v[54:55], v[64:65]
	v_pk_add_f32 v[50:51], v[50:51], v[60:61]
	v_pk_add_f32 v[52:53], v[52:53], v[58:59]
	v_pk_fma_f32 v[62:63], v[178:179], v[62:63], v[186:187]
	v_cvt_pk_f16_f32 v58, v52, v53
	v_cvt_pk_f16_f32 v53, v50, v51
	v_cvt_pk_f16_f32 v51, v54, v55
	v_pk_add_f32 v[56:57], v[56:57], v[62:63]
	v_cndmask_b32_e64 v50, v75, v51, s[72:73]
	v_cvt_pk_f16_f32 v52, v56, v57
	s_nop 0
	v_mov_b32_dpp v54, v50 row_ror:8 row_mask:0xf bank_mask:0xf bound_ctrl:1
	v_cndmask_b32_e64 v50, v54, v75, s[72:73]
	v_cndmask_b32_e64 v54, v51, v54, s[72:73]
	v_cndmask_b32_e64 v51, v74, v52, s[72:73]
	s_nop 1
	v_mov_b32_dpp v55, v51 row_ror:8 row_mask:0xf bank_mask:0xf bound_ctrl:1
	v_cndmask_b32_e64 v51, v55, v74, s[72:73]
	v_cndmask_b32_e64 v55, v52, v55, s[72:73]
	v_cndmask_b32_e64 v52, v73, v53, s[72:73]
	s_nop 1
	v_mov_b32_dpp v56, v52 row_ror:8 row_mask:0xf bank_mask:0xf bound_ctrl:1
	v_cndmask_b32_e64 v52, v56, v73, s[72:73]
	v_cndmask_b32_e64 v56, v53, v56, s[72:73]
	v_cndmask_b32_e64 v53, v72, v58, s[72:73]
	s_nop 1
	v_mov_b32_dpp v57, v53 row_ror:8 row_mask:0xf bank_mask:0xf bound_ctrl:1
	v_cndmask_b32_e64 v53, v57, v72, s[72:73]
	v_cndmask_b32_e64 v57, v58, v57, s[72:73]
	v_add_co_u32_e32 v58, vcc, s2, v164
	s_mov_b32 s2, 0x88000
	s_nop 0
	v_addc_co_u32_e32 v59, vcc, 0, v165, vcc
	global_store_dwordx4 v[58:59], v[50:53], off
	s_nop 1
	v_add_co_u32_e32 v50, vcc, s2, v164
	s_waitcnt vmcnt(2)
	v_cvt_f32_f16_sdwa v53, v82 dst_sel:DWORD dst_unused:UNUSED_PAD src0_sel:WORD_1
	v_addc_co_u32_e32 v51, vcc, 0, v165, vcc
	global_store_dwordx4 v[50:51], v[54:57], off
	v_cvt_f32_f16_e32 v52, v82
	v_cvt_f32_f16_sdwa v51, v83 dst_sel:DWORD dst_unused:UNUSED_PAD src0_sel:WORD_1
	v_cvt_f32_f16_sdwa v55, v81 dst_sel:DWORD dst_unused:UNUSED_PAD src0_sel:WORD_1
	v_cvt_f32_f16_e32 v54, v81
	v_cvt_f32_f16_e32 v50, v83
	v_cvt_f32_f16_sdwa v57, v80 dst_sel:DWORD dst_unused:UNUSED_PAD src0_sel:WORD_1
	v_cvt_f32_f16_e32 v56, v80
	v_sub_f32_e32 v51, v51, v70
	v_sub_f32_e32 v50, v50, v70
	v_sub_f32_e32 v52, v52, v70
	v_sub_f32_e32 v53, v53, v70
	v_sub_f32_e32 v54, v54, v70
	v_sub_f32_e32 v55, v55, v70
	v_pk_mul_f32 v[54:55], v[70:71], v[54:55] op_sel:[1,0]
	v_pk_mul_f32 v[52:53], v[70:71], v[52:53] op_sel:[1,0]
	v_pk_mul_f32 v[50:51], v[70:71], v[50:51] op_sel:[1,0]
	v_sub_f32_e32 v56, v56, v70
	v_sub_f32_e32 v57, v57, v70
	v_pk_fma_f32 v[50:51], v[192:193], v[50:51], v[200:201]
	v_pk_fma_f32 v[52:53], v[188:189], v[52:53], v[194:195]
	v_pk_fma_f32 v[54:55], v[174:175], v[54:55], v[184:185]
	v_pk_mul_f32 v[56:57], v[70:71], v[56:57] op_sel:[1,0]
	v_pk_add_f32 v[48:49], v[48:49], v[54:55]
	v_pk_add_f32 v[42:43], v[42:43], v[52:53]
	v_pk_add_f32 v[44:45], v[44:45], v[50:51]
	v_pk_fma_f32 v[56:57], v[172:173], v[56:57], v[180:181]
	v_cvt_pk_f16_f32 v50, v44, v45
	v_cvt_pk_f16_f32 v51, v42, v43
	v_cvt_pk_f16_f32 v52, v48, v49
	s_waitcnt vmcnt(2)
	v_cvt_f32_f16_sdwa v49, v66 dst_sel:DWORD dst_unused:UNUSED_PAD src0_sel:WORD_1
	v_cvt_f32_f16_e32 v48, v66
	v_cvt_f32_f16_sdwa v45, v68 dst_sel:DWORD dst_unused:UNUSED_PAD src0_sel:WORD_1
	v_cvt_f32_f16_e32 v44, v68
	v_cvt_f32_f16_sdwa v43, v69 dst_sel:DWORD dst_unused:UNUSED_PAD src0_sel:WORD_1
	v_cvt_f32_f16_e32 v42, v69
	v_pk_add_f32 v[46:47], v[46:47], v[56:57]
	v_sub_f32_e32 v44, v44, v70
	v_cvt_pk_f16_f32 v53, v46, v47
	v_cvt_f32_f16_sdwa v47, v67 dst_sel:DWORD dst_unused:UNUSED_PAD src0_sel:WORD_1
	v_cvt_f32_f16_e32 v46, v67
	v_sub_f32_e32 v42, v42, v70
	v_sub_f32_e32 v43, v43, v70
	v_sub_f32_e32 v45, v45, v70
	v_sub_f32_e32 v48, v48, v70
	v_sub_f32_e32 v49, v49, v70
	v_pk_mul_f32 v[48:49], v[70:71], v[48:49] op_sel:[1,0]
	v_pk_mul_f32 v[44:45], v[70:71], v[44:45] op_sel:[1,0]
	v_pk_mul_f32 v[42:43], v[70:71], v[42:43] op_sel:[1,0]
	v_sub_f32_e32 v46, v46, v70
	v_sub_f32_e32 v47, v47, v70
	v_pk_fma_f32 v[42:43], v[196:197], v[42:43], v[202:203]
	v_pk_fma_f32 v[44:45], v[190:191], v[44:45], v[198:199]
	v_pk_fma_f32 v[48:49], v[176:177], v[48:49], v[182:183]
	v_pk_mul_f32 v[46:47], v[70:71], v[46:47] op_sel:[1,0]
	v_pk_add_f32 v[38:39], v[38:39], v[48:49]
	v_pk_add_f32 v[34:35], v[34:35], v[44:45]
	v_pk_add_f32 v[36:37], v[36:37], v[42:43]
	v_pk_fma_f32 v[46:47], v[178:179], v[46:47], v[186:187]
	v_cvt_pk_f16_f32 v42, v36, v37
	v_cvt_pk_f16_f32 v37, v34, v35
	v_cvt_pk_f16_f32 v35, v38, v39
	v_pk_add_f32 v[40:41], v[40:41], v[46:47]
	v_cndmask_b32_e64 v34, v53, v35, s[72:73]
	v_cvt_pk_f16_f32 v36, v40, v41
	s_mov_b32 s2, 0x98000
	v_mov_b32_dpp v38, v34 row_ror:8 row_mask:0xf bank_mask:0xf bound_ctrl:1
;     __device__ __forceinline__ void operator()(Acc& acc, const Unit& u, int wr, int wc, int fr, int fq) const {
;     ...
;             for (int ai = 0; ai < 2; ++ai)
; #pragma unroll
;               for (int mp = 0; mp < 4; mp += 2) {
;                 f32x2 ms[2]; h16x8 rr[2][2];
; #pragma unroll
;                 for (int m = 0; m < 2; ++m) { const int row = row0 + ai * HALF + (mp + m) * 16; ms[m] = st[row];
; #pragma unroll
;                     for (int bj = 0; bj < 2; ++bj) rr[m][bj] = *(const h16x8*)(pre + (size_t)row * DM + colb + bj * BJ); }
;                 asm volatile("" ::: "memory");
; #pragma unroll
;                 for (int m = 0; m < 2; ++m) { u32x4 dd[2];
; #pragma unroll
;                     for (int bj = 0; bj < 2; ++bj) { const f32x8 r = __builtin_convertvector(rr[m][bj], f32x8);
;                         const f32x4 r0 = {r[0], r[1], r[2], r[3]}, r1 = {r[4], r[5], r[6], r[7]};
;                         const f32x4 o0 = ((r0 - ms[m].x) * ms[m].y) * gv[bj][0] + bv[bj][0] + acc[ai][bj][mp + m][0], o1 = ((r1 - ms[m].x) * ms[m].y) * gv[bj][1] + bv[bj][1] + acc[ai][bj][mp + m][1];
;                         const f32x8 o = {o0[0], o0[1], o0[2], o0[3], o1[0], o1[1], o1[2], o1[3]};
;                         dd[bj] = __builtin_bit_cast(u32x4, __builtin_convertvector(o, h16x8)); }
;                     store_pair128(pre + sbase + (size_t)(ai * HALF + (mp + m) * 16) * DM, (size_t)8 * DM, dd[0], dd[1], lo); }
;                 asm volatile("" ::: "memory"); }
	v_cndmask_b32_e64 v34, v38, v53, s[72:73]
	v_cndmask_b32_e64 v38, v35, v38, s[72:73]
	v_cndmask_b32_e64 v35, v52, v36, s[72:73]
	s_nop 1
	v_mov_b32_dpp v39, v35 row_ror:8 row_mask:0xf bank_mask:0xf bound_ctrl:1
	v_cndmask_b32_e64 v35, v39, v52, s[72:73]
	v_cndmask_b32_e64 v39, v36, v39, s[72:73]
	v_cndmask_b32_e64 v36, v51, v37, s[72:73]
	s_nop 1
	v_mov_b32_dpp v40, v36 row_ror:8 row_mask:0xf bank_mask:0xf bound_ctrl:1
	v_cndmask_b32_e64 v36, v40, v51, s[72:73]
	v_cndmask_b32_e64 v40, v37, v40, s[72:73]
	v_cndmask_b32_e64 v37, v50, v42, s[72:73]
	s_nop 1
	v_mov_b32_dpp v41, v37 row_ror:8 row_mask:0xf bank_mask:0xf bound_ctrl:1
	v_cndmask_b32_e64 v37, v41, v50, s[72:73]
	v_cndmask_b32_e64 v41, v42, v41, s[72:73]
	v_add_co_u32_e32 v42, vcc, s82, v164
	s_nop 1
	v_addc_co_u32_e32 v43, vcc, 0, v165, vcc
	global_store_dwordx4 v[42:43], v[34:37], off
	s_nop 1
	v_add_co_u32_e32 v34, vcc, s2, v164
	s_mov_b64 s[2:3], 0xa0000
	s_nop 0
	v_addc_co_u32_e32 v35, vcc, 0, v165, vcc
	global_store_dwordx4 v[34:35], v[38:41], off
	v_add_co_u32_e32 v36, vcc, s83, v204
	global_load_dwordx2 v[52:53], v[170:171], off offset:1280
	s_nop 0
	v_addc_co_u32_e32 v37, vcc, 0, v205, vcc
	v_lshl_add_u64 v[34:35], v[204:205], 0, s[2:3]
	global_load_dwordx4 v[40:43], v[36:37], off
	global_load_dwordx4 v[44:47], v[34:35], off offset:64
	global_load_dwordx2 v[38:39], v[170:171], off offset:1408
	s_mov_b64 s[2:3], 0xb0000
	v_add_co_u32_e32 v36, vcc, s84, v204
	v_lshl_add_u64 v[34:35], v[204:205], 0, s[2:3]
	s_nop 0
	v_addc_co_u32_e32 v37, vcc, 0, v205, vcc
	global_load_dwordx4 v[48:51], v[36:37], off
	s_nop 0
	global_load_dwordx4 v[34:37], v[34:35], off offset:64
	s_mov_b32 s2, 0xa8000
	s_waitcnt vmcnt(4)
	v_cvt_f32_f16_sdwa v57, v40 dst_sel:DWORD dst_unused:UNUSED_PAD src0_sel:WORD_1
	v_cvt_f32_f16_e32 v56, v40
	v_cvt_f32_f16_sdwa v55, v41 dst_sel:DWORD dst_unused:UNUSED_PAD src0_sel:WORD_1
	v_cvt_f32_f16_e32 v54, v41
	v_cvt_f32_f16_sdwa v58, v42 dst_sel:DWORD dst_unused:UNUSED_PAD src0_sel:WORD_1
	v_cvt_f32_f16_e32 v42, v42
	v_cvt_f32_f16_sdwa v41, v43 dst_sel:DWORD dst_unused:UNUSED_PAD src0_sel:WORD_1
	v_cvt_f32_f16_e32 v40, v43
	v_sub_f32_e32 v43, v58, v52
	v_sub_f32_e32 v42, v42, v52
	v_sub_f32_e32 v41, v41, v52
	v_sub_f32_e32 v40, v40, v52
	v_sub_f32_e32 v54, v54, v52
	v_sub_f32_e32 v55, v55, v52
	v_pk_mul_f32 v[54:55], v[52:53], v[54:55] op_sel:[1,0]
	v_pk_mul_f32 v[42:43], v[52:53], v[42:43] op_sel:[1,0]
	v_pk_mul_f32 v[40:41], v[52:53], v[40:41] op_sel:[1,0]
	v_sub_f32_e32 v56, v56, v52
	v_sub_f32_e32 v57, v57, v52
	v_pk_fma_f32 v[40:41], v[192:193], v[40:41], v[200:201]
	v_pk_fma_f32 v[42:43], v[188:189], v[42:43], v[194:195]
	v_pk_fma_f32 v[54:55], v[174:175], v[54:55], v[184:185]
	v_pk_mul_f32 v[56:57], v[52:53], v[56:57] op_sel:[1,0]
	v_pk_add_f32 v[32:33], v[32:33], v[54:55]
	v_pk_add_f32 v[26:27], v[26:27], v[42:43]
	v_pk_add_f32 v[28:29], v[28:29], v[40:41]
	v_pk_fma_f32 v[56:57], v[172:173], v[56:57], v[180:181]
	v_cvt_pk_f16_f32 v40, v28, v29
	v_cvt_pk_f16_f32 v41, v26, v27
	v_cvt_pk_f16_f32 v42, v32, v33
	s_waitcnt vmcnt(3)
	v_cvt_f32_f16_sdwa v33, v44 dst_sel:DWORD dst_unused:UNUSED_PAD src0_sel:WORD_1
	v_cvt_f32_f16_e32 v32, v44
	v_cvt_f32_f16_sdwa v29, v46 dst_sel:DWORD dst_unused:UNUSED_PAD src0_sel:WORD_1
	v_cvt_f32_f16_e32 v28, v46
	v_cvt_f32_f16_sdwa v27, v47 dst_sel:DWORD dst_unused:UNUSED_PAD src0_sel:WORD_1
	v_cvt_f32_f16_e32 v26, v47
	v_pk_add_f32 v[30:31], v[30:31], v[56:57]
	v_sub_f32_e32 v28, v28, v52
	v_cvt_pk_f16_f32 v43, v30, v31
	v_cvt_f32_f16_sdwa v31, v45 dst_sel:DWORD dst_unused:UNUSED_PAD src0_sel:WORD_1
	v_cvt_f32_f16_e32 v30, v45
	v_sub_f32_e32 v26, v26, v52
	v_sub_f32_e32 v27, v27, v52
	v_sub_f32_e32 v29, v29, v52
	v_sub_f32_e32 v32, v32, v52
	v_sub_f32_e32 v33, v33, v52
	v_pk_mul_f32 v[32:33], v[52:53], v[32:33] op_sel:[1,0]
	v_pk_mul_f32 v[28:29], v[52:53], v[28:29] op_sel:[1,0]
	v_pk_mul_f32 v[26:27], v[52:53], v[26:27] op_sel:[1,0]
	v_sub_f32_e32 v30, v30, v52
	v_sub_f32_e32 v31, v31, v52
	v_pk_fma_f32 v[26:27], v[196:197], v[26:27], v[202:203]
	v_pk_fma_f32 v[28:29], v[190:191], v[28:29], v[198:199]
	v_pk_fma_f32 v[32:33], v[176:177], v[32:33], v[182:183]
	v_pk_mul_f32 v[30:31], v[52:53], v[30:31] op_sel:[1,0]
	v_pk_add_f32 v[22:23], v[22:23], v[32:33]
	v_pk_add_f32 v[18:19], v[18:19], v[28:29]
	v_pk_add_f32 v[20:21], v[20:21], v[26:27]
	v_pk_fma_f32 v[30:31], v[178:179], v[30:31], v[186:187]
	v_cvt_pk_f16_f32 v26, v20, v21
	v_cvt_pk_f16_f32 v21, v18, v19
	v_cvt_pk_f16_f32 v19, v22, v23
	v_pk_add_f32 v[24:25], v[24:25], v[30:31]
	v_cndmask_b32_e64 v18, v43, v19, s[72:73]
	v_cvt_pk_f16_f32 v20, v24, v25
	s_nop 0
	v_mov_b32_dpp v22, v18 row_ror:8 row_mask:0xf bank_mask:0xf bound_ctrl:1
	v_cndmask_b32_e64 v18, v22, v43, s[72:73]
	v_cndmask_b32_e64 v22, v19, v22, s[72:73]
	v_cndmask_b32_e64 v19, v42, v20, s[72:73]
	s_nop 1
	v_mov_b32_dpp v23, v19 row_ror:8 row_mask:0xf bank_mask:0xf bound_ctrl:1
	v_cndmask_b32_e64 v19, v23, v42, s[72:73]
	v_cndmask_b32_e64 v23, v20, v23, s[72:73]
	v_cndmask_b32_e64 v20, v41, v21, s[72:73]
	s_nop 1
	v_mov_b32_dpp v24, v20 row_ror:8 row_mask:0xf bank_mask:0xf bound_ctrl:1
	v_cndmask_b32_e64 v20, v24, v41, s[72:73]
	v_cndmask_b32_e64 v24, v21, v24, s[72:73]
	v_cndmask_b32_e64 v21, v40, v26, s[72:73]
	s_nop 1
	v_mov_b32_dpp v25, v21 row_ror:8 row_mask:0xf bank_mask:0xf bound_ctrl:1
	v_cndmask_b32_e64 v21, v25, v40, s[72:73]
	v_cndmask_b32_e64 v25, v26, v25, s[72:73]
	v_add_co_u32_e32 v26, vcc, s83, v164
	s_nop 1
	v_addc_co_u32_e32 v27, vcc, 0, v165, vcc
	global_store_dwordx4 v[26:27], v[18:21], off
	s_nop 1
	v_add_co_u32_e32 v18, vcc, s2, v164
	s_waitcnt vmcnt(2)
;     __device__ __forceinline__ void operator()(Acc& acc, const Unit& u, int wr, int wc, int fr, int fq) const {
;     ...
;             for (int ai = 0; ai < 2; ++ai)
; #pragma unroll
;               for (int mp = 0; mp < 4; mp += 2) {
;                 f32x2 ms[2]; h16x8 rr[2][2];
; #pragma unroll
;                 for (int m = 0; m < 2; ++m) { const int row = row0 + ai * HALF + (mp + m) * 16; ms[m] = st[row];
; #pragma unroll
;                     for (int bj = 0; bj < 2; ++bj) rr[m][bj] = *(const h16x8*)(pre + (size_t)row * DM + colb + bj * BJ); }
;                 asm volatile("" ::: "memory");
; #pragma unroll
;                 for (int m = 0; m < 2; ++m) { u32x4 dd[2];
; #pragma unroll
;                     for (int bj = 0; bj < 2; ++bj) { const f32x8 r = __builtin_convertvector(rr[m][bj], f32x8);
;                         const f32x4 r0 = {r[0], r[1], r[2], r[3]}, r1 = {r[4], r[5], r[6], r[7]};
;                         const f32x4 o0 = ((r0 - ms[m].x) * ms[m].y) * gv[bj][0] + bv[bj][0] + acc[ai][bj][mp + m][0], o1 = ((r1 - ms[m].x) * ms[m].y) * gv[bj][1] + bv[bj][1] + acc[ai][bj][mp + m][1];
;                         const f32x8 o = {o0[0], o0[1], o0[2], o0[3], o1[0], o1[1], o1[2], o1[3]};
;                         dd[bj] = __builtin_bit_cast(u32x4, __builtin_convertvector(o, h16x8)); }
;                     store_pair128(pre + sbase + (size_t)(ai * HALF + (mp + m) * 16) * DM, (size_t)8 * DM, dd[0], dd[1], lo); }
;                 asm volatile("" ::: "memory"); }
	v_cvt_f32_f16_sdwa v21, v50 dst_sel:DWORD dst_unused:UNUSED_PAD src0_sel:WORD_1
	v_addc_co_u32_e32 v19, vcc, 0, v165, vcc
	global_store_dwordx4 v[18:19], v[22:25], off
	v_cvt_f32_f16_e32 v20, v50
	v_cvt_f32_f16_sdwa v19, v51 dst_sel:DWORD dst_unused:UNUSED_PAD src0_sel:WORD_1
	v_cvt_f32_f16_sdwa v23, v49 dst_sel:DWORD dst_unused:UNUSED_PAD src0_sel:WORD_1
	v_cvt_f32_f16_e32 v22, v49
	v_cvt_f32_f16_e32 v18, v51
	v_cvt_f32_f16_sdwa v25, v48 dst_sel:DWORD dst_unused:UNUSED_PAD src0_sel:WORD_1
	v_cvt_f32_f16_e32 v24, v48
	v_sub_f32_e32 v19, v19, v38
	v_sub_f32_e32 v18, v18, v38
	v_sub_f32_e32 v20, v20, v38
	v_sub_f32_e32 v21, v21, v38
	v_sub_f32_e32 v22, v22, v38
	v_sub_f32_e32 v23, v23, v38
	v_pk_mul_f32 v[22:23], v[38:39], v[22:23] op_sel:[1,0]
	v_pk_mul_f32 v[20:21], v[38:39], v[20:21] op_sel:[1,0]
	v_pk_mul_f32 v[18:19], v[38:39], v[18:19] op_sel:[1,0]
	v_sub_f32_e32 v24, v24, v38
	v_sub_f32_e32 v25, v25, v38
	v_pk_fma_f32 v[18:19], v[192:193], v[18:19], v[200:201]
	v_pk_fma_f32 v[20:21], v[188:189], v[20:21], v[194:195]
	v_pk_fma_f32 v[22:23], v[174:175], v[22:23], v[184:185]
	v_pk_mul_f32 v[24:25], v[38:39], v[24:25] op_sel:[1,0]
	v_pk_add_f32 v[16:17], v[16:17], v[22:23]
	v_pk_add_f32 v[10:11], v[10:11], v[20:21]
	v_pk_add_f32 v[12:13], v[12:13], v[18:19]
	v_pk_fma_f32 v[24:25], v[172:173], v[24:25], v[180:181]
	v_cvt_pk_f16_f32 v18, v12, v13
	v_cvt_pk_f16_f32 v19, v10, v11
	v_cvt_pk_f16_f32 v20, v16, v17
	s_waitcnt vmcnt(2)
	v_cvt_f32_f16_sdwa v17, v34 dst_sel:DWORD dst_unused:UNUSED_PAD src0_sel:WORD_1
	v_cvt_f32_f16_e32 v16, v34
	v_cvt_f32_f16_sdwa v13, v36 dst_sel:DWORD dst_unused:UNUSED_PAD src0_sel:WORD_1
	v_cvt_f32_f16_e32 v12, v36
	v_cvt_f32_f16_sdwa v11, v37 dst_sel:DWORD dst_unused:UNUSED_PAD src0_sel:WORD_1
	v_cvt_f32_f16_e32 v10, v37
	v_pk_add_f32 v[14:15], v[14:15], v[24:25]
	v_sub_f32_e32 v12, v12, v38
	v_cvt_pk_f16_f32 v21, v14, v15
	v_cvt_f32_f16_sdwa v15, v35 dst_sel:DWORD dst_unused:UNUSED_PAD src0_sel:WORD_1
	v_cvt_f32_f16_e32 v14, v35
	v_sub_f32_e32 v10, v10, v38
	v_sub_f32_e32 v11, v11, v38
	v_sub_f32_e32 v13, v13, v38
	v_sub_f32_e32 v16, v16, v38
	v_sub_f32_e32 v17, v17, v38
	v_pk_mul_f32 v[16:17], v[38:39], v[16:17] op_sel:[1,0]
	v_pk_mul_f32 v[12:13], v[38:39], v[12:13] op_sel:[1,0]
	v_pk_mul_f32 v[10:11], v[38:39], v[10:11] op_sel:[1,0]
	v_sub_f32_e32 v14, v14, v38
	v_sub_f32_e32 v15, v15, v38
	v_pk_fma_f32 v[10:11], v[196:197], v[10:11], v[202:203]
	v_pk_fma_f32 v[12:13], v[190:191], v[12:13], v[198:199]
	v_pk_fma_f32 v[16:17], v[176:177], v[16:17], v[182:183]
	v_pk_mul_f32 v[14:15], v[38:39], v[14:15] op_sel:[1,0]
	v_pk_add_f32 v[6:7], v[6:7], v[16:17]
	v_pk_add_f32 v[2:3], v[2:3], v[12:13]
	v_pk_add_f32 v[4:5], v[4:5], v[10:11]
	v_pk_fma_f32 v[14:15], v[178:179], v[14:15], v[186:187]
	v_cvt_pk_f16_f32 v10, v4, v5
	v_cvt_pk_f16_f32 v5, v2, v3
	v_cvt_pk_f16_f32 v3, v6, v7
	v_pk_add_f32 v[8:9], v[8:9], v[14:15]
	v_cndmask_b32_e64 v2, v21, v3, s[72:73]
	v_cvt_pk_f16_f32 v4, v8, v9
	s_nop 0
	v_mov_b32_dpp v6, v2 row_ror:8 row_mask:0xf bank_mask:0xf bound_ctrl:1
	v_cndmask_b32_e64 v2, v6, v21, s[72:73]
	v_cndmask_b32_e64 v6, v3, v6, s[72:73]
	v_cndmask_b32_e64 v3, v20, v4, s[72:73]
	s_nop 1
	v_mov_b32_dpp v7, v3 row_ror:8 row_mask:0xf bank_mask:0xf bound_ctrl:1
	v_cndmask_b32_e64 v3, v7, v20, s[72:73]
	v_cndmask_b32_e64 v7, v4, v7, s[72:73]
	v_cndmask_b32_e64 v4, v19, v5, s[72:73]
	s_nop 1
	v_mov_b32_dpp v8, v4 row_ror:8 row_mask:0xf bank_mask:0xf bound_ctrl:1
	v_cndmask_b32_e64 v4, v8, v19, s[72:73]
	v_cndmask_b32_e64 v8, v5, v8, s[72:73]
	v_cndmask_b32_e64 v5, v18, v10, s[72:73]
	s_nop 1
	v_mov_b32_dpp v9, v5 row_ror:8 row_mask:0xf bank_mask:0xf bound_ctrl:1
	v_cndmask_b32_e64 v5, v9, v18, s[72:73]
	v_cndmask_b32_e64 v9, v10, v9, s[72:73]
	v_add_co_u32_e32 v10, vcc, 0xb0000, v164
	s_nop 1
	v_addc_co_u32_e32 v11, vcc, 0, v165, vcc
	global_store_dwordx4 v[10:11], v[2:5], off
	s_nop 1
	v_add_co_u32_e32 v2, vcc, 0xb8000, v164
	s_nop 1
	v_addc_co_u32_e32 v3, vcc, 0, v165, vcc
	global_store_dwordx4 v[2:3], v[6:9], off

;     __device__ __forceinline__ void operator()(Acc& acc, const Unit& u, int wr, int wc, int fr, int fq) const {
;         const int row0 = u.pm * BM + wr * 64 + fr, colb = u.pn * BM + wc * 64 + 8 * fq;
;         const bool lo = fr < 8; const size_t sbase = (size_t)(row0 - fr + (fr & 7)) * DM + colb + (lo ? 0 : BJ);
;         f32x4 gv[2][2], bv[2][2];
;         if (!x) {
; #pragma unroll
;             for (int bj = 0; bj < 2; ++bj)
; #pragma unroll
;                 for (int n = 0; n < 2; ++n) { gv[bj][n] = *(const f32x4*)(gam + colb + bj * BJ + 4 * n) * DN_ALPHA; bv[bj][n] = *(const f32x4*)(bet + colb + bj * BJ + 4 * n) * DN_ALPHA; }
;         }
;         if (x) {
; #pragma unroll
;             for (int ai = 0; ai < 2; ++ai)
; #pragma unroll
;                 for (int m = 0; m < 4; ++m) { const size_t ro = (size_t)(row0 + ai * HALF + m * 16) * DM + colb; u32x4 dd[2];
; #pragma unroll
;                     for (int bj = 0; bj < 2; ++bj) { const f32x4 r0 = *(const f32x4*)(x + ro + bj * BJ), r1 = *(const f32x4*)(x + ro + bj * BJ + 4);
;                         const f32x4 o0 = r0 * DN_ALPHA + acc[ai][bj][m][0], o1 = r1 * DN_ALPHA + acc[ai][bj][m][1];
;                         const f32x8 o = {o0[0], o0[1], o0[2], o0[3], o1[0], o1[1], o1[2], o1[3]};
;                         dd[bj] = __builtin_bit_cast(u32x4, __builtin_convertvector(o, h16x8)); }
;                     store_pair128(pre + sbase + (size_t)(ai * HALF + m * 16) * DM, (size_t)8 * DM, dd[0], dd[1], lo);
;                     if (m & 1) asm volatile("" ::: "memory"); }
;         } else {
; #pragma unroll
;             for (int ai = 0; ai < 2; ++ai)
; #pragma unroll
;               for (int mp = 0; mp < 4; mp += 2) {
;                 f32x2 ms[2]; h16x8 rr[2][2];
; #pragma unroll
;                 for (int m = 0; m < 2; ++m) { const int row = row0 + ai * HALF + (mp + m) * 16; ms[m] = st[row];
; #pragma unroll
;                     for (int bj = 0; bj < 2; ++bj) rr[m][bj] = *(const h16x8*)(pre + (size_t)row * DM + colb + bj * BJ); }
;                 asm volatile("" ::: "memory");
; #pragma unroll
;                 for (int m = 0; m < 2; ++m) { u32x4 dd[2];
; #pragma unroll
;                     for (int bj = 0; bj < 2; ++bj) { const f32x8 r = __builtin_convertvector(rr[m][bj], f32x8);
;                         const f32x4 r0 = {r[0], r[1], r[2], r[3]}, r1 = {r[4], r[5], r[6], r[7]};
.LBB0_1051:
	v_lshl_or_b32 v154, s10, 8, v223
	v_ashrrev_i32_e32 v155, 31, v154
	v_lshlrev_b64 v[132:133], 2, v[154:155]
	v_lshl_add_u64 v[156:157], s[12:13], 0, v[132:133]
	v_lshl_add_u64 v[178:179], s[14:15], 0, v[132:133]
	global_load_dwordx4 v[132:135], v[156:157], off offset:16
	global_load_dwordx4 v[136:139], v[156:157], off
	s_lshl_b32 s2, s41, 8
	s_add_i32 s2, s2, s35
	v_or_b32_e32 v202, s2, v220
	v_or_b32_e32 v206, s2, v222
	s_mov_b32 s2, 0x3fd744fd
	v_lshlrev_b64 v[210:211], 1, v[154:155]
	v_ashrrev_i32_e32 v203, 31, v202
	v_lshl_add_u64 v[204:205], s[88:89], 0, v[210:211]
	v_lshl_add_u64 v[198:199], v[202:203], 3, s[66:67]
	v_ashrrev_i32_e32 v207, 31, v206
	v_readlane_b32 s46, v254, 18
	v_readlane_b32 s43, v249, 44
	v_readlane_b32 s47, v254, 19
	global_load_dwordx4 v[232:235], v[178:179], off offset:16
	global_load_dwordx4 v[236:239], v[178:179], off
	global_load_dwordx4 v[240:243], v[156:157], off offset:144
	global_load_dwordx4 v[244:247], v[156:157], off offset:128
	global_load_dwordx4 v[154:157], v[178:179], off offset:144
	global_load_dwordx4 v[226:229], v[178:179], off offset:128
	s_waitcnt vmcnt(0)
	v_pk_mul_f32 v[184:185], v[134:135], s[2:3] op_sel_hi:[1,0]
	v_pk_mul_f32 v[166:167], v[138:139], s[2:3] op_sel_hi:[1,0]
	v_pk_mul_f32 v[168:169], v[136:137], s[2:3] op_sel_hi:[1,0]
	v_mov_b64_e32 v[136:137], v[232:233]
	v_mov_b64_e32 v[138:139], v[234:235]
	v_mov_b64_e32 v[140:141], v[236:237]
	v_mov_b64_e32 v[142:143], v[238:239]
	v_pk_mul_f32 v[186:187], v[132:133], s[2:3] op_sel_hi:[1,0]
	v_pk_mul_f32 v[190:191], v[138:139], s[2:3] op_sel_hi:[1,0]
	v_pk_mul_f32 v[192:193], v[136:137], s[2:3] op_sel_hi:[1,0]
	v_mov_b64_e32 v[132:133], v[240:241]
	v_mov_b64_e32 v[134:135], v[242:243]
	v_mov_b64_e32 v[136:137], v[244:245]
	v_mov_b64_e32 v[138:139], v[246:247]
	v_pk_mul_f32 v[174:175], v[142:143], s[2:3] op_sel_hi:[1,0]
	v_pk_mul_f32 v[176:177], v[140:141], s[2:3] op_sel_hi:[1,0]
	v_pk_mul_f32 v[182:183], v[132:133], s[2:3] op_sel_hi:[1,0]
	v_pk_mul_f32 v[172:173], v[138:139], s[2:3] op_sel_hi:[1,0]
	v_pk_mul_f32 v[170:171], v[136:137], s[2:3] op_sel_hi:[1,0]
	v_mov_b64_e32 v[136:137], v[154:155]
	v_mov_b64_e32 v[138:139], v[156:157]
	v_mov_b64_e32 v[140:141], v[226:227]
	v_mov_b64_e32 v[142:143], v[228:229]
	v_lshlrev_b64 v[132:133], 12, v[202:203]
	v_lshl_add_u64 v[200:201], v[204:205], 0, v[132:133]
	global_load_dwordx2 v[212:213], v[198:199], off
	v_or_b32_e32 v132, 16, v202
	v_ashrrev_i32_e32 v133, 31, v132
	v_pk_mul_f32 v[188:189], v[134:135], s[2:3] op_sel_hi:[1,0]
	v_lshl_add_u64 v[134:135], v[132:133], 3, s[66:67]
	v_lshlrev_b64 v[132:133], 12, v[132:133]
	v_lshl_add_u64 v[132:133], v[204:205], 0, v[132:133]
	s_waitcnt vmcnt(2)
	v_pk_mul_f32 v[194:195], v[138:139], s[2:3] op_sel_hi:[1,0]
	s_waitcnt vmcnt(1)
	v_pk_mul_f32 v[180:181], v[142:143], s[2:3] op_sel_hi:[1,0]
	v_pk_mul_f32 v[178:179], v[140:141], s[2:3] op_sel_hi:[1,0]
	global_load_dwordx4 v[154:157], v[200:201], off
	global_load_dwordx4 v[140:143], v[200:201], off offset:64
	v_pk_mul_f32 v[196:197], v[136:137], s[2:3] op_sel_hi:[1,0]
	global_load_dwordx2 v[208:209], v[134:135], off
	global_load_dwordx4 v[136:139], v[132:133], off
	s_nop 0
	global_load_dwordx4 v[132:135], v[132:133], off offset:64
	s_mov_b32 s2, 0x8000
	s_waitcnt vmcnt(4)
	v_cvt_f32_f16_sdwa v227, v156 dst_sel:DWORD dst_unused:UNUSED_PAD src0_sel:WORD_1
	v_cvt_f32_f16_e32 v226, v156
	v_cvt_f32_f16_sdwa v228, v155 dst_sel:DWORD dst_unused:UNUSED_PAD src0_sel:WORD_1
	v_cvt_f32_f16_e32 v156, v155
	v_cvt_f32_f16_sdwa v203, v154 dst_sel:DWORD dst_unused:UNUSED_PAD src0_sel:WORD_1
	v_cvt_f32_f16_e32 v225, v154
	v_cvt_f32_f16_sdwa v155, v157 dst_sel:DWORD dst_unused:UNUSED_PAD src0_sel:WORD_1
	v_cvt_f32_f16_e32 v154, v157
	v_sub_f32_e32 v156, v156, v212
	v_sub_f32_e32 v157, v228, v212
	v_sub_f32_e32 v226, v226, v212
	v_sub_f32_e32 v227, v227, v212
	v_sub_f32_e32 v154, v154, v212
	v_sub_f32_e32 v155, v155, v212
	v_pk_mul_f32 v[226:227], v[212:213], v[226:227] op_sel:[1,0]
	v_pk_mul_f32 v[156:157], v[212:213], v[156:157] op_sel:[1,0]
	v_pk_mul_f32 v[154:155], v[212:213], v[154:155] op_sel:[1,0]
	v_pk_fma_f32 v[156:157], v[166:167], v[156:157], v[174:175]
	v_pk_fma_f32 v[226:227], v[186:187], v[226:227], v[192:193]
	v_pk_fma_f32 v[154:155], v[184:185], v[154:155], v[190:191]
	v_pk_add_f32 v[130:131], v[130:131], v[156:157]
	v_pk_add_f32 v[124:125], v[124:125], v[226:227]
	v_sub_f32_e32 v228, v225, v212
	v_sub_f32_e32 v229, v203, v212
	v_pk_add_f32 v[126:127], v[126:127], v[154:155]
	v_cvt_pk_f16_f32 v155, v130, v131
	v_cvt_pk_f16_f32 v156, v124, v125
	s_waitcnt vmcnt(3)
;     __device__ __forceinline__ void operator()(Acc& acc, const Unit& u, int wr, int wc, int fr, int fq) const {
;     ...
;             for (int ai = 0; ai < 2; ++ai)
; #pragma unroll
;               for (int mp = 0; mp < 4; mp += 2) {
;                 f32x2 ms[2]; h16x8 rr[2][2];
; #pragma unroll
;                 for (int m = 0; m < 2; ++m) { const int row = row0 + ai * HALF + (mp + m) * 16; ms[m] = st[row];
; #pragma unroll
;                     for (int bj = 0; bj < 2; ++bj) rr[m][bj] = *(const h16x8*)(pre + (size_t)row * DM + colb + bj * BJ); }
;                 asm volatile("" ::: "memory");
; #pragma unroll
;                 for (int m = 0; m < 2; ++m) { u32x4 dd[2];
; #pragma unroll
;                     for (int bj = 0; bj < 2; ++bj) { const f32x8 r = __builtin_convertvector(rr[m][bj], f32x8);
;                         const f32x4 r0 = {r[0], r[1], r[2], r[3]}, r1 = {r[4], r[5], r[6], r[7]};
;                         const f32x4 o0 = ((r0 - ms[m].x) * ms[m].y) * gv[bj][0] + bv[bj][0] + acc[ai][bj][mp + m][0], o1 = ((r1 - ms[m].x) * ms[m].y) * gv[bj][1] + bv[bj][1] + acc[ai][bj][mp + m][1];
;                         const f32x8 o = {o0[0], o0[1], o0[2], o0[3], o1[0], o1[1], o1[2], o1[3]};
;                         dd[bj] = __builtin_bit_cast(u32x4, __builtin_convertvector(o, h16x8)); }
;                     store_pair128(pre + sbase + (size_t)(ai * HALF + (mp + m) * 16) * DM, (size_t)8 * DM, dd[0], dd[1], lo); }
;                 asm volatile("" ::: "memory"); }
	v_cvt_f32_f16_sdwa v131, v140 dst_sel:DWORD dst_unused:UNUSED_PAD src0_sel:WORD_1
	v_cvt_f32_f16_e32 v130, v140
	v_cvt_f32_f16_sdwa v125, v143 dst_sel:DWORD dst_unused:UNUSED_PAD src0_sel:WORD_1
	v_cvt_f32_f16_e32 v124, v143
	v_pk_mul_f32 v[228:229], v[212:213], v[228:229] op_sel:[1,0]
	v_cvt_pk_f16_f32 v154, v126, v127
	v_pk_fma_f32 v[228:229], v[168:169], v[228:229], v[176:177]
	v_cvt_f32_f16_sdwa v127, v141 dst_sel:DWORD dst_unused:UNUSED_PAD src0_sel:WORD_1
	v_cvt_f32_f16_e32 v126, v141
	v_pk_add_f32 v[128:129], v[128:129], v[228:229]
	v_sub_f32_e32 v124, v124, v212
	v_cvt_pk_f16_f32 v157, v128, v129
	v_cvt_f32_f16_sdwa v129, v142 dst_sel:DWORD dst_unused:UNUSED_PAD src0_sel:WORD_1
	v_cvt_f32_f16_e32 v128, v142
	v_sub_f32_e32 v125, v125, v212
	v_sub_f32_e32 v130, v130, v212
	v_sub_f32_e32 v131, v131, v212
	v_pk_mul_f32 v[130:131], v[212:213], v[130:131] op_sel:[1,0]
	v_pk_mul_f32 v[124:125], v[212:213], v[124:125] op_sel:[1,0]
	v_sub_f32_e32 v126, v126, v212
	v_sub_f32_e32 v127, v127, v212
	v_pk_fma_f32 v[124:125], v[188:189], v[124:125], v[194:195]
	v_pk_fma_f32 v[130:131], v[170:171], v[130:131], v[178:179]
	v_pk_mul_f32 v[126:127], v[212:213], v[126:127] op_sel:[1,0]
	v_pk_add_f32 v[118:119], v[118:119], v[124:125]
	v_pk_add_f32 v[120:121], v[120:121], v[130:131]
	v_sub_f32_e32 v128, v128, v212
	v_sub_f32_e32 v129, v129, v212
	v_pk_fma_f32 v[126:127], v[172:173], v[126:127], v[180:181]
	v_cvt_pk_f16_f32 v125, v118, v119
	v_cvt_pk_f16_f32 v119, v120, v121
	v_pk_mul_f32 v[128:129], v[212:213], v[128:129] op_sel:[1,0]
	v_pk_add_f32 v[122:123], v[122:123], v[126:127]
	v_cndmask_b32_e64 v118, v157, v119, s[0:1]
	v_pk_fma_f32 v[128:129], v[182:183], v[128:129], v[196:197]
	v_cvt_pk_f16_f32 v123, v122, v123
	v_mov_b32_dpp v120, v118 row_ror:8 row_mask:0xf bank_mask:0xf bound_ctrl:1
	v_pk_add_f32 v[116:117], v[116:117], v[128:129]
	v_cndmask_b32_e64 v122, v119, v120, s[0:1]
	v_cndmask_b32_e64 v119, v155, v123, s[0:1]
	v_cvt_pk_f16_f32 v124, v116, v117
	v_cndmask_b32_e64 v118, v120, v157, s[0:1]
	v_mov_b32_dpp v120, v119 row_ror:8 row_mask:0xf bank_mask:0xf bound_ctrl:1
	v_cndmask_b32_e64 v119, v120, v155, s[0:1]
	v_cndmask_b32_e64 v123, v123, v120, s[0:1]
	v_cndmask_b32_e64 v120, v156, v124, s[0:1]
	v_lshlrev_b64 v[116:117], 12, v[206:207]
	v_lshl_add_u64 v[116:117], s[88:89], 0, v[116:117]
	v_mov_b32_dpp v121, v120 row_ror:8 row_mask:0xf bank_mask:0xf bound_ctrl:1
	v_cndmask_b32_e64 v120, v121, v156, s[0:1]
	v_cndmask_b32_e64 v124, v124, v121, s[0:1]
	v_cndmask_b32_e64 v121, v154, v125, s[0:1]
	v_lshl_add_u64 v[116:117], v[116:117], 0, v[210:211]
	v_lshl_add_u64 v[116:117], v[116:117], 0, v[98:99]
	v_mov_b32_dpp v126, v121 row_ror:8 row_mask:0xf bank_mask:0xf bound_ctrl:1
	v_cndmask_b32_e64 v121, v126, v154, s[0:1]
	global_store_dwordx4 v[116:117], v[118:121], off
	v_cndmask_b32_e64 v125, v125, v126, s[0:1]
	s_nop 0
	v_add_co_u32_e32 v118, vcc, s2, v116
	s_waitcnt vmcnt(2)
	v_cvt_f32_f16_sdwa v121, v137 dst_sel:DWORD dst_unused:UNUSED_PAD src0_sel:WORD_1
	v_addc_co_u32_e32 v119, vcc, 0, v117, vcc
	global_store_dwordx4 v[118:119], v[122:125], off
	v_cvt_f32_f16_e32 v120, v137
	v_cvt_f32_f16_sdwa v119, v139 dst_sel:DWORD dst_unused:UNUSED_PAD src0_sel:WORD_1
	v_cvt_f32_f16_sdwa v125, v136 dst_sel:DWORD dst_unused:UNUSED_PAD src0_sel:WORD_1
	v_cvt_f32_f16_e32 v124, v136
	v_cvt_f32_f16_sdwa v123, v138 dst_sel:DWORD dst_unused:UNUSED_PAD src0_sel:WORD_1
	v_cvt_f32_f16_e32 v122, v138
	v_cvt_f32_f16_e32 v118, v139
	v_sub_f32_e32 v120, v120, v208
	v_sub_f32_e32 v121, v121, v208
	v_sub_f32_e32 v122, v122, v208
	v_sub_f32_e32 v123, v123, v208
	v_sub_f32_e32 v124, v124, v208
	v_sub_f32_e32 v125, v125, v208
	v_sub_f32_e32 v118, v118, v208
	v_sub_f32_e32 v119, v119, v208
	v_pk_mul_f32 v[124:125], v[208:209], v[124:125] op_sel:[1,0]
	v_pk_mul_f32 v[122:123], v[208:209], v[122:123] op_sel:[1,0]
	v_pk_mul_f32 v[120:121], v[208:209], v[120:121] op_sel:[1,0]
	v_pk_mul_f32 v[118:119], v[208:209], v[118:119] op_sel:[1,0]
	v_pk_fma_f32 v[120:121], v[166:167], v[120:121], v[174:175]
	v_pk_fma_f32 v[122:123], v[186:187], v[122:123], v[192:193]
	v_pk_fma_f32 v[124:125], v[168:169], v[124:125], v[176:177]
	v_pk_fma_f32 v[118:119], v[184:185], v[118:119], v[190:191]
	v_pk_add_f32 v[114:115], v[114:115], v[120:121]
	v_pk_add_f32 v[112:113], v[112:113], v[124:125]
	v_pk_add_f32 v[108:109], v[108:109], v[122:123]
	v_pk_add_f32 v[110:111], v[110:111], v[118:119]
	v_cvt_pk_f16_f32 v119, v114, v115
	v_cvt_pk_f16_f32 v120, v108, v109
	v_cvt_pk_f16_f32 v121, v112, v113
	s_waitcnt vmcnt(2)
;     __device__ __forceinline__ void operator()(Acc& acc, const Unit& u, int wr, int wc, int fr, int fq) const {
;     ...
;             for (int ai = 0; ai < 2; ++ai)
; #pragma unroll
;               for (int mp = 0; mp < 4; mp += 2) {
;                 f32x2 ms[2]; h16x8 rr[2][2];
; #pragma unroll
;                 for (int m = 0; m < 2; ++m) { const int row = row0 + ai * HALF + (mp + m) * 16; ms[m] = st[row];
; #pragma unroll
;                     for (int bj = 0; bj < 2; ++bj) rr[m][bj] = *(const h16x8*)(pre + (size_t)row * DM + colb + bj * BJ); }
;                 asm volatile("" ::: "memory");
; #pragma unroll
;                 for (int m = 0; m < 2; ++m) { u32x4 dd[2];
; #pragma unroll
;                     for (int bj = 0; bj < 2; ++bj) { const f32x8 r = __builtin_convertvector(rr[m][bj], f32x8);
;                         const f32x4 r0 = {r[0], r[1], r[2], r[3]}, r1 = {r[4], r[5], r[6], r[7]};
;                         const f32x4 o0 = ((r0 - ms[m].x) * ms[m].y) * gv[bj][0] + bv[bj][0] + acc[ai][bj][mp + m][0], o1 = ((r1 - ms[m].x) * ms[m].y) * gv[bj][1] + bv[bj][1] + acc[ai][bj][mp + m][1];
;                         const f32x8 o = {o0[0], o0[1], o0[2], o0[3], o1[0], o1[1], o1[2], o1[3]};
;                         dd[bj] = __builtin_bit_cast(u32x4, __builtin_convertvector(o, h16x8)); }
;                     store_pair128(pre + sbase + (size_t)(ai * HALF + (mp + m) * 16) * DM, (size_t)8 * DM, dd[0], dd[1], lo); }
;                 asm volatile("" ::: "memory"); }
	v_cvt_f32_f16_sdwa v115, v132 dst_sel:DWORD dst_unused:UNUSED_PAD src0_sel:WORD_1
	v_cvt_f32_f16_e32 v114, v132
	v_cvt_f32_f16_sdwa v113, v134 dst_sel:DWORD dst_unused:UNUSED_PAD src0_sel:WORD_1
	v_cvt_f32_f16_e32 v112, v134
	v_cvt_f32_f16_sdwa v109, v135 dst_sel:DWORD dst_unused:UNUSED_PAD src0_sel:WORD_1
	v_cvt_f32_f16_e32 v108, v135
	v_cvt_pk_f16_f32 v118, v110, v111
	v_cvt_f32_f16_sdwa v111, v133 dst_sel:DWORD dst_unused:UNUSED_PAD src0_sel:WORD_1
	v_cvt_f32_f16_e32 v110, v133
	v_sub_f32_e32 v108, v108, v208
	v_sub_f32_e32 v109, v109, v208
	v_sub_f32_e32 v112, v112, v208
	v_sub_f32_e32 v113, v113, v208
	v_sub_f32_e32 v114, v114, v208
	v_sub_f32_e32 v115, v115, v208
	v_pk_mul_f32 v[114:115], v[208:209], v[114:115] op_sel:[1,0]
	v_pk_mul_f32 v[112:113], v[208:209], v[112:113] op_sel:[1,0]
	v_pk_mul_f32 v[108:109], v[208:209], v[108:109] op_sel:[1,0]
	v_sub_f32_e32 v110, v110, v208
	v_sub_f32_e32 v111, v111, v208
	v_pk_fma_f32 v[108:109], v[188:189], v[108:109], v[194:195]
	v_pk_fma_f32 v[112:113], v[182:183], v[112:113], v[196:197]
	v_pk_fma_f32 v[114:115], v[170:171], v[114:115], v[178:179]
	v_pk_mul_f32 v[110:111], v[208:209], v[110:111] op_sel:[1,0]
	v_pk_add_f32 v[102:103], v[102:103], v[108:109]
	v_pk_add_f32 v[104:105], v[104:105], v[114:115]
	v_pk_add_f32 v[100:101], v[100:101], v[112:113]
	v_pk_fma_f32 v[110:111], v[172:173], v[110:111], v[180:181]
	v_cvt_pk_f16_f32 v108, v102, v103
	v_cvt_pk_f16_f32 v103, v100, v101
	v_cvt_pk_f16_f32 v101, v104, v105
	v_pk_add_f32 v[106:107], v[106:107], v[110:111]
	v_cndmask_b32_e64 v100, v121, v101, s[0:1]
	v_cvt_pk_f16_f32 v102, v106, v107
	s_mov_b32 s2, 0x10000
	v_mov_b32_dpp v104, v100 row_ror:8 row_mask:0xf bank_mask:0xf bound_ctrl:1
	v_cndmask_b32_e64 v100, v104, v121, s[0:1]
	v_cndmask_b32_e64 v104, v101, v104, s[0:1]
	v_cndmask_b32_e64 v101, v119, v102, s[0:1]
	s_nop 1
	v_mov_b32_dpp v105, v101 row_ror:8 row_mask:0xf bank_mask:0xf bound_ctrl:1
	v_cndmask_b32_e64 v101, v105, v119, s[0:1]
	v_cndmask_b32_e64 v105, v102, v105, s[0:1]
	v_cndmask_b32_e64 v102, v120, v103, s[0:1]
	s_nop 1
	v_mov_b32_dpp v106, v102 row_ror:8 row_mask:0xf bank_mask:0xf bound_ctrl:1
	v_cndmask_b32_e64 v102, v106, v120, s[0:1]
	v_cndmask_b32_e64 v106, v103, v106, s[0:1]
	v_cndmask_b32_e64 v103, v118, v108, s[0:1]
	s_nop 1
	v_mov_b32_dpp v107, v103 row_ror:8 row_mask:0xf bank_mask:0xf bound_ctrl:1
	v_cndmask_b32_e64 v103, v107, v118, s[0:1]
	v_cndmask_b32_e64 v107, v108, v107, s[0:1]
	v_add_co_u32_e32 v108, vcc, s2, v116
	s_mov_b32 s2, 0x18000
	s_nop 0
	v_addc_co_u32_e32 v109, vcc, 0, v117, vcc
	global_store_dwordx4 v[108:109], v[100:103], off
	s_nop 1
	v_add_co_u32_e32 v100, vcc, s2, v116
	s_mov_b32 s2, 0x38000
	s_nop 0
	v_addc_co_u32_e32 v101, vcc, 0, v117, vcc
	global_store_dwordx4 v[100:101], v[104:107], off
	v_or_b32_e32 v100, 32, v202
	v_ashrrev_i32_e32 v101, 31, v100
	v_lshl_add_u64 v[102:103], v[100:101], 3, s[66:67]
	v_lshlrev_b64 v[100:101], 12, v[100:101]
	v_lshl_add_u64 v[100:101], v[204:205], 0, v[100:101]
	global_load_dwordx2 v[114:115], v[102:103], off
	global_load_dwordx4 v[106:109], v[100:101], off
	global_load_dwordx4 v[110:113], v[100:101], off offset:64
	v_or_b32_e32 v100, 48, v202
	v_ashrrev_i32_e32 v101, 31, v100
	v_lshl_add_u64 v[102:103], v[100:101], 3, s[66:67]
	v_lshlrev_b64 v[100:101], 12, v[100:101]
	v_lshl_add_u64 v[100:101], v[204:205], 0, v[100:101]
	global_load_dwordx2 v[104:105], v[102:103], off
	global_load_dwordx4 v[118:121], v[100:101], off
	s_nop 0
	global_load_dwordx4 v[100:103], v[100:101], off offset:64
	s_waitcnt vmcnt(4)
	v_cvt_f32_f16_sdwa v125, v106 dst_sel:DWORD dst_unused:UNUSED_PAD src0_sel:WORD_1
	v_cvt_f32_f16_e32 v124, v106
	v_cvt_f32_f16_sdwa v123, v108 dst_sel:DWORD dst_unused:UNUSED_PAD src0_sel:WORD_1
	v_cvt_f32_f16_e32 v122, v108
	v_cvt_f32_f16_sdwa v126, v107 dst_sel:DWORD dst_unused:UNUSED_PAD src0_sel:WORD_1
	v_cvt_f32_f16_e32 v108, v107
	v_cvt_f32_f16_sdwa v107, v109 dst_sel:DWORD dst_unused:UNUSED_PAD src0_sel:WORD_1
	v_cvt_f32_f16_e32 v106, v109
	v_sub_f32_e32 v109, v126, v114
	v_sub_f32_e32 v108, v108, v114
	v_sub_f32_e32 v122, v122, v114
	v_sub_f32_e32 v123, v123, v114
	v_sub_f32_e32 v124, v124, v114
	v_sub_f32_e32 v125, v125, v114
	v_sub_f32_e32 v106, v106, v114
	v_sub_f32_e32 v107, v107, v114
	v_pk_mul_f32 v[124:125], v[114:115], v[124:125] op_sel:[1,0]
	v_pk_mul_f32 v[122:123], v[114:115], v[122:123] op_sel:[1,0]
	v_pk_mul_f32 v[108:109], v[114:115], v[108:109] op_sel:[1,0]
	v_pk_mul_f32 v[106:107], v[114:115], v[106:107] op_sel:[1,0]
	v_pk_fma_f32 v[108:109], v[166:167], v[108:109], v[174:175]
	v_pk_fma_f32 v[122:123], v[186:187], v[122:123], v[192:193]
	v_pk_fma_f32 v[124:125], v[168:169], v[124:125], v[176:177]
	v_pk_fma_f32 v[106:107], v[184:185], v[106:107], v[190:191]
	v_pk_add_f32 v[96:97], v[96:97], v[108:109]
	v_pk_add_f32 v[94:95], v[94:95], v[124:125]
	v_pk_add_f32 v[90:91], v[90:91], v[122:123]
	v_pk_add_f32 v[92:93], v[92:93], v[106:107]
	v_cvt_pk_f16_f32 v107, v96, v97
	v_cvt_pk_f16_f32 v108, v90, v91
	v_cvt_pk_f16_f32 v109, v94, v95
	s_waitcnt vmcnt(3)
;     __device__ __forceinline__ void operator()(Acc& acc, const Unit& u, int wr, int wc, int fr, int fq) const {
;     ...
;             for (int ai = 0; ai < 2; ++ai)
; #pragma unroll
;               for (int mp = 0; mp < 4; mp += 2) {
;                 f32x2 ms[2]; h16x8 rr[2][2];
; #pragma unroll
;                 for (int m = 0; m < 2; ++m) { const int row = row0 + ai * HALF + (mp + m) * 16; ms[m] = st[row];
; #pragma unroll
;                     for (int bj = 0; bj < 2; ++bj) rr[m][bj] = *(const h16x8*)(pre + (size_t)row * DM + colb + bj * BJ); }
;                 asm volatile("" ::: "memory");
; #pragma unroll
;                 for (int m = 0; m < 2; ++m) { u32x4 dd[2];
; #pragma unroll
;                     for (int bj = 0; bj < 2; ++bj) { const f32x8 r = __builtin_convertvector(rr[m][bj], f32x8);
;                         const f32x4 r0 = {r[0], r[1], r[2], r[3]}, r1 = {r[4], r[5], r[6], r[7]};
;                         const f32x4 o0 = ((r0 - ms[m].x) * ms[m].y) * gv[bj][0] + bv[bj][0] + acc[ai][bj][mp + m][0], o1 = ((r1 - ms[m].x) * ms[m].y) * gv[bj][1] + bv[bj][1] + acc[ai][bj][mp + m][1];
;                         const f32x8 o = {o0[0], o0[1], o0[2], o0[3], o1[0], o1[1], o1[2], o1[3]};
;                         dd[bj] = __builtin_bit_cast(u32x4, __builtin_convertvector(o, h16x8)); }
;                     store_pair128(pre + sbase + (size_t)(ai * HALF + (mp + m) * 16) * DM, (size_t)8 * DM, dd[0], dd[1], lo); }
;                 asm volatile("" ::: "memory"); }
	v_cvt_f32_f16_sdwa v97, v110 dst_sel:DWORD dst_unused:UNUSED_PAD src0_sel:WORD_1
	v_cvt_f32_f16_e32 v96, v110
	v_cvt_f32_f16_sdwa v95, v112 dst_sel:DWORD dst_unused:UNUSED_PAD src0_sel:WORD_1
	v_cvt_f32_f16_e32 v94, v112
	v_cvt_f32_f16_sdwa v91, v113 dst_sel:DWORD dst_unused:UNUSED_PAD src0_sel:WORD_1
	v_cvt_f32_f16_e32 v90, v113
	v_cvt_pk_f16_f32 v106, v92, v93
	v_cvt_f32_f16_sdwa v93, v111 dst_sel:DWORD dst_unused:UNUSED_PAD src0_sel:WORD_1
	v_cvt_f32_f16_e32 v92, v111
	v_sub_f32_e32 v90, v90, v114
	v_sub_f32_e32 v91, v91, v114
	v_sub_f32_e32 v94, v94, v114
	v_sub_f32_e32 v95, v95, v114
	v_sub_f32_e32 v96, v96, v114
	v_sub_f32_e32 v97, v97, v114
	v_pk_mul_f32 v[96:97], v[114:115], v[96:97] op_sel:[1,0]
	v_pk_mul_f32 v[94:95], v[114:115], v[94:95] op_sel:[1,0]
	v_pk_mul_f32 v[90:91], v[114:115], v[90:91] op_sel:[1,0]
	v_sub_f32_e32 v92, v92, v114
	v_sub_f32_e32 v93, v93, v114
	v_pk_fma_f32 v[90:91], v[188:189], v[90:91], v[194:195]
	v_pk_fma_f32 v[94:95], v[182:183], v[94:95], v[196:197]
	v_pk_fma_f32 v[96:97], v[170:171], v[96:97], v[178:179]
	v_pk_mul_f32 v[92:93], v[114:115], v[92:93] op_sel:[1,0]
	v_pk_add_f32 v[84:85], v[84:85], v[90:91]
	v_pk_add_f32 v[86:87], v[86:87], v[96:97]
	v_pk_add_f32 v[82:83], v[82:83], v[94:95]
	v_pk_fma_f32 v[92:93], v[172:173], v[92:93], v[180:181]
	v_cvt_pk_f16_f32 v90, v84, v85
	v_cvt_pk_f16_f32 v85, v82, v83
	v_cvt_pk_f16_f32 v83, v86, v87
	v_pk_add_f32 v[88:89], v[88:89], v[92:93]
	v_cndmask_b32_e64 v82, v109, v83, s[0:1]
	v_cvt_pk_f16_f32 v84, v88, v89
	s_nop 0
	v_mov_b32_dpp v86, v82 row_ror:8 row_mask:0xf bank_mask:0xf bound_ctrl:1
	v_cndmask_b32_e64 v82, v86, v109, s[0:1]
	v_cndmask_b32_e64 v86, v83, v86, s[0:1]
	v_cndmask_b32_e64 v83, v107, v84, s[0:1]
	s_nop 1
	v_mov_b32_dpp v87, v83 row_ror:8 row_mask:0xf bank_mask:0xf bound_ctrl:1
	v_cndmask_b32_e64 v83, v87, v107, s[0:1]
	v_cndmask_b32_e64 v87, v84, v87, s[0:1]
	v_cndmask_b32_e64 v84, v108, v85, s[0:1]
	s_nop 1
	v_mov_b32_dpp v88, v84 row_ror:8 row_mask:0xf bank_mask:0xf bound_ctrl:1
	v_cndmask_b32_e64 v84, v88, v108, s[0:1]
	v_cndmask_b32_e64 v88, v85, v88, s[0:1]
	v_cndmask_b32_e64 v85, v106, v90, s[0:1]
	s_nop 1
	v_mov_b32_dpp v89, v85 row_ror:8 row_mask:0xf bank_mask:0xf bound_ctrl:1
	v_cndmask_b32_e64 v85, v89, v106, s[0:1]
	v_cndmask_b32_e64 v89, v90, v89, s[0:1]
	v_add_co_u32_e32 v90, vcc, s74, v116
	s_nop 1
	v_addc_co_u32_e32 v91, vcc, 0, v117, vcc
	global_store_dwordx4 v[90:91], v[82:85], off
	s_nop 1
	v_add_co_u32_e32 v82, vcc, s75, v116
	s_waitcnt vmcnt(2)
	v_cvt_f32_f16_sdwa v85, v119 dst_sel:DWORD dst_unused:UNUSED_PAD src0_sel:WORD_1
	v_addc_co_u32_e32 v83, vcc, 0, v117, vcc
	global_store_dwordx4 v[82:83], v[86:89], off
	v_cvt_f32_f16_e32 v84, v119
	v_cvt_f32_f16_sdwa v83, v121 dst_sel:DWORD dst_unused:UNUSED_PAD src0_sel:WORD_1
	v_cvt_f32_f16_sdwa v89, v118 dst_sel:DWORD dst_unused:UNUSED_PAD src0_sel:WORD_1
	v_cvt_f32_f16_e32 v88, v118
	v_cvt_f32_f16_sdwa v87, v120 dst_sel:DWORD dst_unused:UNUSED_PAD src0_sel:WORD_1
	v_cvt_f32_f16_e32 v86, v120
	v_cvt_f32_f16_e32 v82, v121
	v_sub_f32_e32 v84, v84, v104
	v_sub_f32_e32 v85, v85, v104
	v_sub_f32_e32 v86, v86, v104
	v_sub_f32_e32 v87, v87, v104
	v_sub_f32_e32 v88, v88, v104
	v_sub_f32_e32 v89, v89, v104
	v_sub_f32_e32 v82, v82, v104
	v_sub_f32_e32 v83, v83, v104
	v_pk_mul_f32 v[88:89], v[104:105], v[88:89] op_sel:[1,0]
	v_pk_mul_f32 v[86:87], v[104:105], v[86:87] op_sel:[1,0]
	v_pk_mul_f32 v[84:85], v[104:105], v[84:85] op_sel:[1,0]
	v_pk_mul_f32 v[82:83], v[104:105], v[82:83] op_sel:[1,0]
	v_pk_fma_f32 v[84:85], v[166:167], v[84:85], v[174:175]
	v_pk_fma_f32 v[86:87], v[186:187], v[86:87], v[192:193]
	v_pk_fma_f32 v[88:89], v[168:169], v[88:89], v[176:177]
	v_pk_fma_f32 v[82:83], v[184:185], v[82:83], v[190:191]
	v_pk_add_f32 v[80:81], v[80:81], v[84:85]
	v_pk_add_f32 v[78:79], v[78:79], v[88:89]
	v_pk_add_f32 v[74:75], v[74:75], v[86:87]
	v_pk_add_f32 v[76:77], v[76:77], v[82:83]
	v_cvt_pk_f16_f32 v83, v80, v81
	v_cvt_pk_f16_f32 v84, v74, v75
	v_cvt_pk_f16_f32 v85, v78, v79
	s_waitcnt vmcnt(2)
	v_cvt_f32_f16_sdwa v81, v100 dst_sel:DWORD dst_unused:UNUSED_PAD src0_sel:WORD_1
	v_cvt_f32_f16_e32 v80, v100
	v_cvt_f32_f16_sdwa v79, v102 dst_sel:DWORD dst_unused:UNUSED_PAD src0_sel:WORD_1
	v_cvt_f32_f16_e32 v78, v102
	v_cvt_f32_f16_sdwa v75, v103 dst_sel:DWORD dst_unused:UNUSED_PAD src0_sel:WORD_1
	v_cvt_f32_f16_e32 v74, v103
	v_cvt_pk_f16_f32 v82, v76, v77
	v_cvt_f32_f16_sdwa v77, v101 dst_sel:DWORD dst_unused:UNUSED_PAD src0_sel:WORD_1
	v_cvt_f32_f16_e32 v76, v101
	v_sub_f32_e32 v74, v74, v104
	v_sub_f32_e32 v75, v75, v104
	v_sub_f32_e32 v78, v78, v104
	v_sub_f32_e32 v79, v79, v104
	v_sub_f32_e32 v80, v80, v104
	v_sub_f32_e32 v81, v81, v104
	v_pk_mul_f32 v[80:81], v[104:105], v[80:81] op_sel:[1,0]
	v_pk_mul_f32 v[78:79], v[104:105], v[78:79] op_sel:[1,0]
	v_pk_mul_f32 v[74:75], v[104:105], v[74:75] op_sel:[1,0]
	v_sub_f32_e32 v76, v76, v104
	v_sub_f32_e32 v77, v77, v104
	v_pk_fma_f32 v[74:75], v[188:189], v[74:75], v[194:195]
	v_pk_fma_f32 v[78:79], v[182:183], v[78:79], v[196:197]
	v_pk_fma_f32 v[80:81], v[170:171], v[80:81], v[178:179]
	v_pk_mul_f32 v[76:77], v[104:105], v[76:77] op_sel:[1,0]
	v_pk_add_f32 v[68:69], v[68:69], v[74:75]
	v_pk_add_f32 v[70:71], v[70:71], v[80:81]
	v_pk_add_f32 v[66:67], v[66:67], v[78:79]
	v_pk_fma_f32 v[76:77], v[172:173], v[76:77], v[180:181]
	v_cvt_pk_f16_f32 v74, v68, v69
	v_cvt_pk_f16_f32 v69, v66, v67
	v_cvt_pk_f16_f32 v67, v70, v71
	v_pk_add_f32 v[72:73], v[72:73], v[76:77]
	v_cndmask_b32_e64 v66, v85, v67, s[0:1]
	v_cvt_pk_f16_f32 v68, v72, v73
	s_nop 0
	v_mov_b32_dpp v70, v66 row_ror:8 row_mask:0xf bank_mask:0xf bound_ctrl:1
;     __device__ __forceinline__ void operator()(Acc& acc, const Unit& u, int wr, int wc, int fr, int fq) const {
;     ...
;             for (int ai = 0; ai < 2; ++ai)
; #pragma unroll
;               for (int mp = 0; mp < 4; mp += 2) {
;                 f32x2 ms[2]; h16x8 rr[2][2];
; #pragma unroll
;                 for (int m = 0; m < 2; ++m) { const int row = row0 + ai * HALF + (mp + m) * 16; ms[m] = st[row];
; #pragma unroll
;                     for (int bj = 0; bj < 2; ++bj) rr[m][bj] = *(const h16x8*)(pre + (size_t)row * DM + colb + bj * BJ); }
;                 asm volatile("" ::: "memory");
; #pragma unroll
;                 for (int m = 0; m < 2; ++m) { u32x4 dd[2];
; #pragma unroll
;                     for (int bj = 0; bj < 2; ++bj) { const f32x8 r = __builtin_convertvector(rr[m][bj], f32x8);
;                         const f32x4 r0 = {r[0], r[1], r[2], r[3]}, r1 = {r[4], r[5], r[6], r[7]};
;                         const f32x4 o0 = ((r0 - ms[m].x) * ms[m].y) * gv[bj][0] + bv[bj][0] + acc[ai][bj][mp + m][0], o1 = ((r1 - ms[m].x) * ms[m].y) * gv[bj][1] + bv[bj][1] + acc[ai][bj][mp + m][1];
;                         const f32x8 o = {o0[0], o0[1], o0[2], o0[3], o1[0], o1[1], o1[2], o1[3]};
;                         dd[bj] = __builtin_bit_cast(u32x4, __builtin_convertvector(o, h16x8)); }
;                     store_pair128(pre + sbase + (size_t)(ai * HALF + (mp + m) * 16) * DM, (size_t)8 * DM, dd[0], dd[1], lo); }
;                 asm volatile("" ::: "memory"); }
	v_cndmask_b32_e64 v66, v70, v85, s[0:1]
	v_cndmask_b32_e64 v70, v67, v70, s[0:1]
	v_cndmask_b32_e64 v67, v83, v68, s[0:1]
	s_nop 1
	v_mov_b32_dpp v71, v67 row_ror:8 row_mask:0xf bank_mask:0xf bound_ctrl:1
	v_cndmask_b32_e64 v67, v71, v83, s[0:1]
	v_cndmask_b32_e64 v71, v68, v71, s[0:1]
	v_cndmask_b32_e64 v68, v84, v69, s[0:1]
	s_nop 1
	v_mov_b32_dpp v72, v68 row_ror:8 row_mask:0xf bank_mask:0xf bound_ctrl:1
	v_cndmask_b32_e64 v68, v72, v84, s[0:1]
	v_cndmask_b32_e64 v72, v69, v72, s[0:1]
	v_cndmask_b32_e64 v69, v82, v74, s[0:1]
	s_nop 1
	v_mov_b32_dpp v73, v69 row_ror:8 row_mask:0xf bank_mask:0xf bound_ctrl:1
	v_cndmask_b32_e64 v69, v73, v82, s[0:1]
	v_cndmask_b32_e64 v73, v74, v73, s[0:1]
	v_add_co_u32_e32 v74, vcc, s78, v116
	s_nop 1
	v_addc_co_u32_e32 v75, vcc, 0, v117, vcc
	global_store_dwordx4 v[74:75], v[66:69], off
	s_nop 1
	v_add_co_u32_e32 v66, vcc, s2, v116
	s_mov_b64 s[2:3], 0x80000
	s_nop 0
	v_addc_co_u32_e32 v67, vcc, 0, v117, vcc
	global_store_dwordx4 v[66:67], v[70:73], off
	v_lshl_add_u64 v[66:67], v[200:201], 0, s[2:3]
	s_mov_b32 s2, 0x80000
	v_add_co_u32_e32 v68, vcc, s2, v200
	global_load_dwordx2 v[84:85], v[198:199], off offset:1024
	s_nop 0
	v_addc_co_u32_e32 v69, vcc, 0, v201, vcc
	global_load_dwordx4 v[72:75], v[68:69], off
	global_load_dwordx4 v[76:79], v[66:67], off offset:64
	global_load_dwordx2 v[70:71], v[198:199], off offset:1152
	v_add_co_u32_e32 v68, vcc, s56, v200
	v_lshl_add_u64 v[66:67], v[200:201], 0, s[84:85]
	s_nop 0
	v_addc_co_u32_e32 v69, vcc, 0, v201, vcc
	global_load_dwordx4 v[80:83], v[68:69], off
	s_nop 0
	global_load_dwordx4 v[66:69], v[66:67], off offset:64
	s_waitcnt vmcnt(4)
	v_cvt_f32_f16_sdwa v89, v72 dst_sel:DWORD dst_unused:UNUSED_PAD src0_sel:WORD_1
	v_cvt_f32_f16_e32 v88, v72
	v_cvt_f32_f16_sdwa v87, v73 dst_sel:DWORD dst_unused:UNUSED_PAD src0_sel:WORD_1
	v_cvt_f32_f16_e32 v86, v73
	v_cvt_f32_f16_sdwa v90, v74 dst_sel:DWORD dst_unused:UNUSED_PAD src0_sel:WORD_1
	v_cvt_f32_f16_e32 v74, v74
	v_cvt_f32_f16_sdwa v73, v75 dst_sel:DWORD dst_unused:UNUSED_PAD src0_sel:WORD_1
	v_cvt_f32_f16_e32 v72, v75
	v_sub_f32_e32 v75, v90, v84
	v_sub_f32_e32 v74, v74, v84
	v_sub_f32_e32 v86, v86, v84
	v_sub_f32_e32 v87, v87, v84
	v_sub_f32_e32 v88, v88, v84
	v_sub_f32_e32 v89, v89, v84
	v_sub_f32_e32 v72, v72, v84
	v_sub_f32_e32 v73, v73, v84
	v_pk_mul_f32 v[88:89], v[84:85], v[88:89] op_sel:[1,0]
	v_pk_mul_f32 v[86:87], v[84:85], v[86:87] op_sel:[1,0]
	v_pk_mul_f32 v[74:75], v[84:85], v[74:75] op_sel:[1,0]
	v_pk_mul_f32 v[72:73], v[84:85], v[72:73] op_sel:[1,0]
	v_pk_fma_f32 v[74:75], v[186:187], v[74:75], v[192:193]
	v_pk_fma_f32 v[86:87], v[166:167], v[86:87], v[174:175]
	v_pk_fma_f32 v[88:89], v[168:169], v[88:89], v[176:177]
	v_pk_fma_f32 v[72:73], v[184:185], v[72:73], v[190:191]
	v_pk_add_f32 v[62:63], v[62:63], v[88:89]
	v_pk_add_f32 v[64:65], v[64:65], v[86:87]
	v_pk_add_f32 v[58:59], v[58:59], v[74:75]
	v_pk_add_f32 v[60:61], v[60:61], v[72:73]
	v_cvt_pk_f16_f32 v73, v58, v59
	v_cvt_pk_f16_f32 v74, v64, v65
	v_cvt_pk_f16_f32 v75, v62, v63
	s_waitcnt vmcnt(3)
	v_cvt_f32_f16_sdwa v65, v76 dst_sel:DWORD dst_unused:UNUSED_PAD src0_sel:WORD_1
	v_cvt_f32_f16_e32 v64, v76
	v_cvt_f32_f16_sdwa v63, v78 dst_sel:DWORD dst_unused:UNUSED_PAD src0_sel:WORD_1
	v_cvt_f32_f16_e32 v62, v78
	v_cvt_f32_f16_sdwa v59, v79 dst_sel:DWORD dst_unused:UNUSED_PAD src0_sel:WORD_1
	v_cvt_f32_f16_e32 v58, v79
	v_cvt_pk_f16_f32 v72, v60, v61
	v_cvt_f32_f16_sdwa v61, v77 dst_sel:DWORD dst_unused:UNUSED_PAD src0_sel:WORD_1
	v_cvt_f32_f16_e32 v60, v77
	v_sub_f32_e32 v58, v58, v84
	v_sub_f32_e32 v59, v59, v84
	v_sub_f32_e32 v62, v62, v84
	v_sub_f32_e32 v63, v63, v84
	v_sub_f32_e32 v64, v64, v84
	v_sub_f32_e32 v65, v65, v84
	v_pk_mul_f32 v[64:65], v[84:85], v[64:65] op_sel:[1,0]
	v_pk_mul_f32 v[62:63], v[84:85], v[62:63] op_sel:[1,0]
	v_pk_mul_f32 v[58:59], v[84:85], v[58:59] op_sel:[1,0]
	v_sub_f32_e32 v60, v60, v84
	v_sub_f32_e32 v61, v61, v84
	v_pk_fma_f32 v[58:59], v[188:189], v[58:59], v[194:195]
	v_pk_fma_f32 v[62:63], v[182:183], v[62:63], v[196:197]
	v_pk_fma_f32 v[64:65], v[170:171], v[64:65], v[178:179]
	v_pk_mul_f32 v[60:61], v[84:85], v[60:61] op_sel:[1,0]
	v_pk_add_f32 v[52:53], v[52:53], v[58:59]
	v_pk_add_f32 v[54:55], v[54:55], v[64:65]
	v_pk_add_f32 v[50:51], v[50:51], v[62:63]
	v_pk_fma_f32 v[60:61], v[172:173], v[60:61], v[180:181]
	v_cvt_pk_f16_f32 v58, v52, v53
	v_cvt_pk_f16_f32 v53, v50, v51
	v_cvt_pk_f16_f32 v51, v54, v55
	v_pk_add_f32 v[56:57], v[56:57], v[60:61]
	v_cndmask_b32_e64 v50, v75, v51, s[0:1]
	v_cvt_pk_f16_f32 v52, v56, v57
	s_nop 0
	v_mov_b32_dpp v54, v50 row_ror:8 row_mask:0xf bank_mask:0xf bound_ctrl:1
	v_cndmask_b32_e64 v50, v54, v75, s[0:1]
	v_cndmask_b32_e64 v54, v51, v54, s[0:1]
	v_cndmask_b32_e64 v51, v74, v52, s[0:1]
	s_nop 1
	v_mov_b32_dpp v55, v51 row_ror:8 row_mask:0xf bank_mask:0xf bound_ctrl:1
	v_cndmask_b32_e64 v51, v55, v74, s[0:1]
	v_cndmask_b32_e64 v55, v52, v55, s[0:1]
	v_cndmask_b32_e64 v52, v73, v53, s[0:1]
	s_nop 1
	v_mov_b32_dpp v56, v52 row_ror:8 row_mask:0xf bank_mask:0xf bound_ctrl:1
	v_cndmask_b32_e64 v52, v56, v73, s[0:1]
	v_cndmask_b32_e64 v56, v53, v56, s[0:1]
	v_cndmask_b32_e64 v53, v72, v58, s[0:1]
	s_nop 1
	v_mov_b32_dpp v57, v53 row_ror:8 row_mask:0xf bank_mask:0xf bound_ctrl:1
	v_cndmask_b32_e64 v53, v57, v72, s[0:1]
	v_cndmask_b32_e64 v57, v58, v57, s[0:1]
	v_add_co_u32_e32 v58, vcc, s2, v116
	s_mov_b32 s2, 0x88000
	s_nop 0
	v_addc_co_u32_e32 v59, vcc, 0, v117, vcc
	global_store_dwordx4 v[58:59], v[50:53], off
	s_nop 1
	v_add_co_u32_e32 v50, vcc, s2, v116
	s_waitcnt vmcnt(2)
;     __device__ __forceinline__ void operator()(Acc& acc, const Unit& u, int wr, int wc, int fr, int fq) const {
;     ...
;             for (int ai = 0; ai < 2; ++ai)
; #pragma unroll
;               for (int mp = 0; mp < 4; mp += 2) {
;                 f32x2 ms[2]; h16x8 rr[2][2];
; #pragma unroll
;                 for (int m = 0; m < 2; ++m) { const int row = row0 + ai * HALF + (mp + m) * 16; ms[m] = st[row];
; #pragma unroll
;                     for (int bj = 0; bj < 2; ++bj) rr[m][bj] = *(const h16x8*)(pre + (size_t)row * DM + colb + bj * BJ); }
;                 asm volatile("" ::: "memory");
; #pragma unroll
;                 for (int m = 0; m < 2; ++m) { u32x4 dd[2];
; #pragma unroll
;                     for (int bj = 0; bj < 2; ++bj) { const f32x8 r = __builtin_convertvector(rr[m][bj], f32x8);
;                         const f32x4 r0 = {r[0], r[1], r[2], r[3]}, r1 = {r[4], r[5], r[6], r[7]};
;                         const f32x4 o0 = ((r0 - ms[m].x) * ms[m].y) * gv[bj][0] + bv[bj][0] + acc[ai][bj][mp + m][0], o1 = ((r1 - ms[m].x) * ms[m].y) * gv[bj][1] + bv[bj][1] + acc[ai][bj][mp + m][1];
;                         const f32x8 o = {o0[0], o0[1], o0[2], o0[3], o1[0], o1[1], o1[2], o1[3]};
;                         dd[bj] = __builtin_bit_cast(u32x4, __builtin_convertvector(o, h16x8)); }
;                     store_pair128(pre + sbase + (size_t)(ai * HALF + (mp + m) * 16) * DM, (size_t)8 * DM, dd[0], dd[1], lo); }
;                 asm volatile("" ::: "memory"); }
	v_cvt_f32_f16_sdwa v53, v82 dst_sel:DWORD dst_unused:UNUSED_PAD src0_sel:WORD_1
	v_addc_co_u32_e32 v51, vcc, 0, v117, vcc
	global_store_dwordx4 v[50:51], v[54:57], off
	v_cvt_f32_f16_e32 v52, v82
	v_cvt_f32_f16_sdwa v51, v83 dst_sel:DWORD dst_unused:UNUSED_PAD src0_sel:WORD_1
	v_cvt_f32_f16_sdwa v57, v80 dst_sel:DWORD dst_unused:UNUSED_PAD src0_sel:WORD_1
	v_cvt_f32_f16_e32 v56, v80
	v_cvt_f32_f16_sdwa v55, v81 dst_sel:DWORD dst_unused:UNUSED_PAD src0_sel:WORD_1
	v_cvt_f32_f16_e32 v54, v81
	v_cvt_f32_f16_e32 v50, v83
	v_sub_f32_e32 v52, v52, v70
	v_sub_f32_e32 v53, v53, v70
	v_sub_f32_e32 v54, v54, v70
	v_sub_f32_e32 v55, v55, v70
	v_sub_f32_e32 v56, v56, v70
	v_sub_f32_e32 v57, v57, v70
	v_sub_f32_e32 v50, v50, v70
	v_sub_f32_e32 v51, v51, v70
	v_pk_mul_f32 v[56:57], v[70:71], v[56:57] op_sel:[1,0]
	v_pk_mul_f32 v[54:55], v[70:71], v[54:55] op_sel:[1,0]
	v_pk_mul_f32 v[52:53], v[70:71], v[52:53] op_sel:[1,0]
	v_pk_mul_f32 v[50:51], v[70:71], v[50:51] op_sel:[1,0]
	v_pk_fma_f32 v[52:53], v[186:187], v[52:53], v[192:193]
	v_pk_fma_f32 v[54:55], v[166:167], v[54:55], v[174:175]
	v_pk_fma_f32 v[56:57], v[168:169], v[56:57], v[176:177]
	v_pk_fma_f32 v[50:51], v[184:185], v[50:51], v[190:191]
	v_pk_add_f32 v[46:47], v[46:47], v[56:57]
	v_pk_add_f32 v[48:49], v[48:49], v[54:55]
	v_pk_add_f32 v[42:43], v[42:43], v[52:53]
	v_pk_add_f32 v[44:45], v[44:45], v[50:51]
	v_cvt_pk_f16_f32 v51, v42, v43
	v_cvt_pk_f16_f32 v52, v48, v49
	v_cvt_pk_f16_f32 v53, v46, v47
	s_waitcnt vmcnt(2)
	v_cvt_f32_f16_sdwa v49, v66 dst_sel:DWORD dst_unused:UNUSED_PAD src0_sel:WORD_1
	v_cvt_f32_f16_e32 v48, v66
	v_cvt_f32_f16_sdwa v47, v68 dst_sel:DWORD dst_unused:UNUSED_PAD src0_sel:WORD_1
	v_cvt_f32_f16_e32 v46, v68
	v_cvt_f32_f16_sdwa v43, v69 dst_sel:DWORD dst_unused:UNUSED_PAD src0_sel:WORD_1
	v_cvt_f32_f16_e32 v42, v69
	v_cvt_pk_f16_f32 v50, v44, v45
	v_cvt_f32_f16_sdwa v45, v67 dst_sel:DWORD dst_unused:UNUSED_PAD src0_sel:WORD_1
	v_cvt_f32_f16_e32 v44, v67
	v_sub_f32_e32 v42, v42, v70
	v_sub_f32_e32 v43, v43, v70
	v_sub_f32_e32 v46, v46, v70
	v_sub_f32_e32 v47, v47, v70
	v_sub_f32_e32 v48, v48, v70
	v_sub_f32_e32 v49, v49, v70
	v_pk_mul_f32 v[48:49], v[70:71], v[48:49] op_sel:[1,0]
	v_pk_mul_f32 v[46:47], v[70:71], v[46:47] op_sel:[1,0]
	v_pk_mul_f32 v[42:43], v[70:71], v[42:43] op_sel:[1,0]
	v_sub_f32_e32 v44, v44, v70
	v_sub_f32_e32 v45, v45, v70
	v_pk_fma_f32 v[42:43], v[188:189], v[42:43], v[194:195]
	v_pk_fma_f32 v[46:47], v[182:183], v[46:47], v[196:197]
	v_pk_fma_f32 v[48:49], v[170:171], v[48:49], v[178:179]
	v_pk_mul_f32 v[44:45], v[70:71], v[44:45] op_sel:[1,0]
	v_pk_add_f32 v[36:37], v[36:37], v[42:43]
	v_pk_add_f32 v[38:39], v[38:39], v[48:49]
	v_pk_add_f32 v[34:35], v[34:35], v[46:47]
	v_pk_fma_f32 v[44:45], v[172:173], v[44:45], v[180:181]
	v_cvt_pk_f16_f32 v42, v36, v37
	v_cvt_pk_f16_f32 v37, v34, v35
	v_cvt_pk_f16_f32 v35, v38, v39
	v_pk_add_f32 v[40:41], v[40:41], v[44:45]
	v_cndmask_b32_e64 v34, v53, v35, s[0:1]
	v_cvt_pk_f16_f32 v36, v40, v41
	s_mov_b32 s2, 0x98000
	v_mov_b32_dpp v38, v34 row_ror:8 row_mask:0xf bank_mask:0xf bound_ctrl:1
	v_cndmask_b32_e64 v34, v38, v53, s[0:1]
	v_cndmask_b32_e64 v38, v35, v38, s[0:1]
	v_cndmask_b32_e64 v35, v52, v36, s[0:1]
	s_nop 1
	v_mov_b32_dpp v39, v35 row_ror:8 row_mask:0xf bank_mask:0xf bound_ctrl:1
	v_cndmask_b32_e64 v35, v39, v52, s[0:1]
	v_cndmask_b32_e64 v39, v36, v39, s[0:1]
	v_cndmask_b32_e64 v36, v51, v37, s[0:1]
	s_nop 1
	v_mov_b32_dpp v40, v36 row_ror:8 row_mask:0xf bank_mask:0xf bound_ctrl:1
	v_cndmask_b32_e64 v36, v40, v51, s[0:1]
	v_cndmask_b32_e64 v40, v37, v40, s[0:1]
	v_cndmask_b32_e64 v37, v50, v42, s[0:1]
	s_nop 1
	v_mov_b32_dpp v41, v37 row_ror:8 row_mask:0xf bank_mask:0xf bound_ctrl:1
	v_cndmask_b32_e64 v37, v41, v50, s[0:1]
	v_cndmask_b32_e64 v41, v42, v41, s[0:1]
	v_add_co_u32_e32 v42, vcc, s56, v116
	s_nop 1
	v_addc_co_u32_e32 v43, vcc, 0, v117, vcc
	global_store_dwordx4 v[42:43], v[34:37], off
	s_nop 1
	v_add_co_u32_e32 v34, vcc, s2, v116
	s_mov_b64 s[2:3], 0xb0000
	s_nop 0
	v_addc_co_u32_e32 v35, vcc, 0, v117, vcc
	global_store_dwordx4 v[34:35], v[38:41], off
	v_add_co_u32_e32 v36, vcc, s72, v200
	global_load_dwordx2 v[52:53], v[198:199], off offset:1280
	s_nop 0
	v_addc_co_u32_e32 v37, vcc, 0, v201, vcc
	v_lshl_add_u64 v[34:35], v[200:201], 0, s[86:87]
	global_load_dwordx4 v[40:43], v[36:37], off
	global_load_dwordx4 v[44:47], v[34:35], off offset:64
	global_load_dwordx2 v[38:39], v[198:199], off offset:1408
	v_add_co_u32_e32 v36, vcc, s73, v200
	v_lshl_add_u64 v[34:35], v[200:201], 0, s[2:3]
	s_nop 0
	v_addc_co_u32_e32 v37, vcc, 0, v201, vcc
	global_load_dwordx4 v[48:51], v[36:37], off
	s_nop 0
	global_load_dwordx4 v[34:37], v[34:35], off offset:64
	s_mov_b32 s2, 0xa8000
	s_waitcnt vmcnt(4)
	v_cvt_f32_f16_sdwa v57, v40 dst_sel:DWORD dst_unused:UNUSED_PAD src0_sel:WORD_1
	v_cvt_f32_f16_e32 v56, v40
	v_cvt_f32_f16_sdwa v55, v41 dst_sel:DWORD dst_unused:UNUSED_PAD src0_sel:WORD_1
	v_cvt_f32_f16_e32 v54, v41
	v_cvt_f32_f16_sdwa v58, v42 dst_sel:DWORD dst_unused:UNUSED_PAD src0_sel:WORD_1
	v_cvt_f32_f16_e32 v42, v42
	v_cvt_f32_f16_sdwa v41, v43 dst_sel:DWORD dst_unused:UNUSED_PAD src0_sel:WORD_1
	v_cvt_f32_f16_e32 v40, v43
	v_sub_f32_e32 v43, v58, v52
	v_sub_f32_e32 v42, v42, v52
	v_sub_f32_e32 v54, v54, v52
	v_sub_f32_e32 v55, v55, v52
	v_sub_f32_e32 v56, v56, v52
	v_sub_f32_e32 v57, v57, v52
	v_sub_f32_e32 v40, v40, v52
	v_sub_f32_e32 v41, v41, v52
	v_pk_mul_f32 v[56:57], v[52:53], v[56:57] op_sel:[1,0]
	v_pk_mul_f32 v[54:55], v[52:53], v[54:55] op_sel:[1,0]
	v_pk_mul_f32 v[42:43], v[52:53], v[42:43] op_sel:[1,0]
	v_pk_mul_f32 v[40:41], v[52:53], v[40:41] op_sel:[1,0]
	v_pk_fma_f32 v[42:43], v[186:187], v[42:43], v[192:193]
	v_pk_fma_f32 v[54:55], v[166:167], v[54:55], v[174:175]
	v_pk_fma_f32 v[56:57], v[168:169], v[56:57], v[176:177]
	v_pk_fma_f32 v[40:41], v[184:185], v[40:41], v[190:191]
	v_pk_add_f32 v[30:31], v[30:31], v[56:57]
	v_pk_add_f32 v[32:33], v[32:33], v[54:55]
	v_pk_add_f32 v[26:27], v[26:27], v[42:43]
	v_pk_add_f32 v[28:29], v[28:29], v[40:41]
	v_cvt_pk_f16_f32 v41, v26, v27
	v_cvt_pk_f16_f32 v42, v32, v33
	v_cvt_pk_f16_f32 v43, v30, v31
	s_waitcnt vmcnt(3)
; #define PG8_BAR __builtin_amdgcn_s_barrier()
; template <class Epi, class Sched>
; __device__ __forceinline__ void gemm_phase(LAS unsigned char* lds, const Gemm g, const Sched& S, const Epi& E) {
;     ...
;         if (!has_next) break;
;         if (!E.keep(cur)) {
;             bf16x8 zf = {0, 0, 0, 0, 0, 0, 0, 0}; asm volatile("" : "+v"(zf));
; #pragma unroll
;             for (int a = 0; a < 2; ++a)
; #pragma unroll
;                 for (int b = 0; b < 2; ++b)
; #pragma unroll
;                     for (int m = 0; m < 4; ++m)
; #pragma unroll
;                         for (int n = 0; n < 2; ++n) acc[a][b][m][n] = __builtin_amdgcn_mfma_f32_16x16x32_bf16(zf, zf, (f32x4){0.f, 0.f, 0.f, 0.f}, 0, 0, 0);
;         }
;         cur = nxt; cA = nA; cB = nB; ++ui;
;         if (wr == 1) PG8_BAR;
;     __device__ __forceinline__ void operator()(Acc& acc, const Unit& u, int wr, int wc, int fr, int fq) const {
;     ...
;             for (int ai = 0; ai < 2; ++ai)
; #pragma unroll
;               for (int mp = 0; mp < 4; mp += 2) {
;                 f32x2 ms[2]; h16x8 rr[2][2];
; #pragma unroll
;                 for (int m = 0; m < 2; ++m) { const int row = row0 + ai * HALF + (mp + m) * 16; ms[m] = st[row];
; #pragma unroll
;                     for (int bj = 0; bj < 2; ++bj) rr[m][bj] = *(const h16x8*)(pre + (size_t)row * DM + colb + bj * BJ); }
;                 asm volatile("" ::: "memory");
; #pragma unroll
;                 for (int m = 0; m < 2; ++m) { u32x4 dd[2];
; #pragma unroll
;                     for (int bj = 0; bj < 2; ++bj) { const f32x8 r = __builtin_convertvector(rr[m][bj], f32x8);
;                         const f32x4 r0 = {r[0], r[1], r[2], r[3]}, r1 = {r[4], r[5], r[6], r[7]};
;                         const f32x4 o0 = ((r0 - ms[m].x) * ms[m].y) * gv[bj][0] + bv[bj][0] + acc[ai][bj][mp + m][0], o1 = ((r1 - ms[m].x) * ms[m].y) * gv[bj][1] + bv[bj][1] + acc[ai][bj][mp + m][1];
;                         const f32x8 o = {o0[0], o0[1], o0[2], o0[3], o1[0], o1[1], o1[2], o1[3]};
;                         dd[bj] = __builtin_bit_cast(u32x4, __builtin_convertvector(o, h16x8)); }
;                     store_pair128(pre + sbase + (size_t)(ai * HALF + (mp + m) * 16) * DM, (size_t)8 * DM, dd[0], dd[1], lo); }
;                 asm volatile("" ::: "memory"); }
	v_cvt_f32_f16_sdwa v33, v44 dst_sel:DWORD dst_unused:UNUSED_PAD src0_sel:WORD_1
	v_cvt_f32_f16_e32 v32, v44
	v_cvt_f32_f16_sdwa v31, v46 dst_sel:DWORD dst_unused:UNUSED_PAD src0_sel:WORD_1
	v_cvt_f32_f16_e32 v30, v46
	v_cvt_f32_f16_sdwa v27, v47 dst_sel:DWORD dst_unused:UNUSED_PAD src0_sel:WORD_1
	v_cvt_f32_f16_e32 v26, v47
	v_cvt_pk_f16_f32 v40, v28, v29
	v_cvt_f32_f16_sdwa v29, v45 dst_sel:DWORD dst_unused:UNUSED_PAD src0_sel:WORD_1
	v_cvt_f32_f16_e32 v28, v45
	v_sub_f32_e32 v26, v26, v52
	v_sub_f32_e32 v27, v27, v52
	v_sub_f32_e32 v30, v30, v52
	v_sub_f32_e32 v31, v31, v52
	v_sub_f32_e32 v32, v32, v52
	v_sub_f32_e32 v33, v33, v52
	v_pk_mul_f32 v[32:33], v[52:53], v[32:33] op_sel:[1,0]
	v_pk_mul_f32 v[30:31], v[52:53], v[30:31] op_sel:[1,0]
	v_pk_mul_f32 v[26:27], v[52:53], v[26:27] op_sel:[1,0]
	v_sub_f32_e32 v28, v28, v52
	v_sub_f32_e32 v29, v29, v52
	v_pk_fma_f32 v[26:27], v[188:189], v[26:27], v[194:195]
	v_pk_fma_f32 v[30:31], v[182:183], v[30:31], v[196:197]
	v_pk_fma_f32 v[32:33], v[170:171], v[32:33], v[178:179]
	v_pk_mul_f32 v[28:29], v[52:53], v[28:29] op_sel:[1,0]
	v_pk_add_f32 v[20:21], v[20:21], v[26:27]
	v_pk_add_f32 v[22:23], v[22:23], v[32:33]
	v_pk_add_f32 v[18:19], v[18:19], v[30:31]
	v_pk_fma_f32 v[28:29], v[172:173], v[28:29], v[180:181]
	v_cvt_pk_f16_f32 v26, v20, v21
	v_cvt_pk_f16_f32 v21, v18, v19
	v_cvt_pk_f16_f32 v19, v22, v23
	v_pk_add_f32 v[24:25], v[24:25], v[28:29]
	v_cndmask_b32_e64 v18, v43, v19, s[0:1]
	v_cvt_pk_f16_f32 v20, v24, v25
	s_nop 0
	v_mov_b32_dpp v22, v18 row_ror:8 row_mask:0xf bank_mask:0xf bound_ctrl:1
	v_cndmask_b32_e64 v18, v22, v43, s[0:1]
	v_cndmask_b32_e64 v22, v19, v22, s[0:1]
	v_cndmask_b32_e64 v19, v42, v20, s[0:1]
	s_nop 1
	v_mov_b32_dpp v23, v19 row_ror:8 row_mask:0xf bank_mask:0xf bound_ctrl:1
	v_cndmask_b32_e64 v19, v23, v42, s[0:1]
	v_cndmask_b32_e64 v23, v20, v23, s[0:1]
	v_cndmask_b32_e64 v20, v41, v21, s[0:1]
	s_nop 1
	v_mov_b32_dpp v24, v20 row_ror:8 row_mask:0xf bank_mask:0xf bound_ctrl:1
	v_cndmask_b32_e64 v20, v24, v41, s[0:1]
	v_cndmask_b32_e64 v24, v21, v24, s[0:1]
	v_cndmask_b32_e64 v21, v40, v26, s[0:1]
	s_nop 1
	v_mov_b32_dpp v25, v21 row_ror:8 row_mask:0xf bank_mask:0xf bound_ctrl:1
	v_cndmask_b32_e64 v21, v25, v40, s[0:1]
	v_cndmask_b32_e64 v25, v26, v25, s[0:1]
	v_add_co_u32_e32 v26, vcc, s72, v116
	s_nop 1
	v_addc_co_u32_e32 v27, vcc, 0, v117, vcc
	global_store_dwordx4 v[26:27], v[18:21], off
	s_nop 1
	v_add_co_u32_e32 v18, vcc, s2, v116
	s_waitcnt vmcnt(2)
	v_cvt_f32_f16_sdwa v21, v50 dst_sel:DWORD dst_unused:UNUSED_PAD src0_sel:WORD_1
	v_addc_co_u32_e32 v19, vcc, 0, v117, vcc
	global_store_dwordx4 v[18:19], v[22:25], off
	v_cvt_f32_f16_e32 v20, v50
	v_cvt_f32_f16_sdwa v19, v51 dst_sel:DWORD dst_unused:UNUSED_PAD src0_sel:WORD_1
	v_cvt_f32_f16_sdwa v25, v48 dst_sel:DWORD dst_unused:UNUSED_PAD src0_sel:WORD_1
	v_cvt_f32_f16_e32 v24, v48
	v_cvt_f32_f16_sdwa v23, v49 dst_sel:DWORD dst_unused:UNUSED_PAD src0_sel:WORD_1
	v_cvt_f32_f16_e32 v22, v49
	v_cvt_f32_f16_e32 v18, v51
	v_sub_f32_e32 v20, v20, v38
	v_sub_f32_e32 v21, v21, v38
	v_sub_f32_e32 v22, v22, v38
	v_sub_f32_e32 v23, v23, v38
	v_sub_f32_e32 v24, v24, v38
	v_sub_f32_e32 v25, v25, v38
	v_sub_f32_e32 v18, v18, v38
	v_sub_f32_e32 v19, v19, v38
	v_pk_mul_f32 v[24:25], v[38:39], v[24:25] op_sel:[1,0]
	v_pk_mul_f32 v[22:23], v[38:39], v[22:23] op_sel:[1,0]
	v_pk_mul_f32 v[20:21], v[38:39], v[20:21] op_sel:[1,0]
	v_pk_mul_f32 v[18:19], v[38:39], v[18:19] op_sel:[1,0]
	v_pk_fma_f32 v[20:21], v[186:187], v[20:21], v[192:193]
	v_pk_fma_f32 v[22:23], v[166:167], v[22:23], v[174:175]
	v_pk_fma_f32 v[24:25], v[168:169], v[24:25], v[176:177]
	v_pk_fma_f32 v[18:19], v[184:185], v[18:19], v[190:191]
	v_pk_add_f32 v[14:15], v[14:15], v[24:25]
	v_pk_add_f32 v[16:17], v[16:17], v[22:23]
	v_pk_add_f32 v[10:11], v[10:11], v[20:21]
	v_pk_add_f32 v[12:13], v[12:13], v[18:19]
	v_cvt_pk_f16_f32 v19, v10, v11
	v_cvt_pk_f16_f32 v20, v16, v17
	v_cvt_pk_f16_f32 v21, v14, v15
	s_waitcnt vmcnt(2)
	v_cvt_f32_f16_sdwa v17, v34 dst_sel:DWORD dst_unused:UNUSED_PAD src0_sel:WORD_1
	v_cvt_f32_f16_e32 v16, v34
	v_cvt_f32_f16_sdwa v15, v36 dst_sel:DWORD dst_unused:UNUSED_PAD src0_sel:WORD_1
	v_cvt_f32_f16_e32 v14, v36
	v_cvt_f32_f16_sdwa v11, v37 dst_sel:DWORD dst_unused:UNUSED_PAD src0_sel:WORD_1
	v_cvt_f32_f16_e32 v10, v37
	v_cvt_pk_f16_f32 v18, v12, v13
	v_cvt_f32_f16_sdwa v13, v35 dst_sel:DWORD dst_unused:UNUSED_PAD src0_sel:WORD_1
	v_cvt_f32_f16_e32 v12, v35
	v_sub_f32_e32 v10, v10, v38
	v_sub_f32_e32 v11, v11, v38
	v_sub_f32_e32 v14, v14, v38
	v_sub_f32_e32 v15, v15, v38
	v_sub_f32_e32 v16, v16, v38
	v_sub_f32_e32 v17, v17, v38
	v_pk_mul_f32 v[16:17], v[38:39], v[16:17] op_sel:[1,0]
	v_pk_mul_f32 v[14:15], v[38:39], v[14:15] op_sel:[1,0]
	v_pk_mul_f32 v[10:11], v[38:39], v[10:11] op_sel:[1,0]
	v_sub_f32_e32 v12, v12, v38
	v_sub_f32_e32 v13, v13, v38
	v_pk_fma_f32 v[10:11], v[188:189], v[10:11], v[194:195]
	v_pk_fma_f32 v[14:15], v[182:183], v[14:15], v[196:197]
	v_pk_fma_f32 v[16:17], v[170:171], v[16:17], v[178:179]
	v_pk_mul_f32 v[12:13], v[38:39], v[12:13] op_sel:[1,0]
	v_pk_add_f32 v[4:5], v[4:5], v[10:11]
	v_pk_add_f32 v[6:7], v[6:7], v[16:17]
	v_pk_add_f32 v[2:3], v[2:3], v[14:15]
	v_pk_fma_f32 v[12:13], v[172:173], v[12:13], v[180:181]
	v_cvt_pk_f16_f32 v10, v4, v5
	v_cvt_pk_f16_f32 v5, v2, v3
	v_cvt_pk_f16_f32 v3, v6, v7
	v_pk_add_f32 v[8:9], v[8:9], v[12:13]
	v_cndmask_b32_e64 v2, v21, v3, s[0:1]
	v_cvt_pk_f16_f32 v4, v8, v9
	s_mov_b64 s[2:3], -1
	v_mov_b32_dpp v6, v2 row_ror:8 row_mask:0xf bank_mask:0xf bound_ctrl:1
	v_cndmask_b32_e64 v2, v6, v21, s[0:1]
	v_cndmask_b32_e64 v6, v3, v6, s[0:1]
	v_cndmask_b32_e64 v3, v20, v4, s[0:1]
	s_nop 1
	v_mov_b32_dpp v7, v3 row_ror:8 row_mask:0xf bank_mask:0xf bound_ctrl:1
	v_cndmask_b32_e64 v3, v7, v20, s[0:1]
	v_cndmask_b32_e64 v7, v4, v7, s[0:1]
	v_cndmask_b32_e64 v4, v19, v5, s[0:1]
	s_nop 1
	v_mov_b32_dpp v8, v4 row_ror:8 row_mask:0xf bank_mask:0xf bound_ctrl:1
	v_cndmask_b32_e64 v4, v8, v19, s[0:1]
	v_cndmask_b32_e64 v8, v5, v8, s[0:1]
	v_cndmask_b32_e64 v5, v18, v10, s[0:1]
	s_nop 1
	v_mov_b32_dpp v9, v5 row_ror:8 row_mask:0xf bank_mask:0xf bound_ctrl:1
	v_cndmask_b32_e64 v5, v9, v18, s[0:1]
	v_cndmask_b32_e64 v9, v10, v9, s[0:1]
	v_add_co_u32_e32 v10, vcc, 0xb0000, v116
	s_nop 1
	v_addc_co_u32_e32 v11, vcc, 0, v117, vcc
	global_store_dwordx4 v[10:11], v[2:5], off
	s_nop 1
	v_add_co_u32_e32 v2, vcc, 0xb8000, v116
	s_nop 1
	v_addc_co_u32_e32 v3, vcc, 0, v117, vcc
	global_store_dwordx4 v[2:3], v[6:9], off
	s_and_b64 vcc, exec, s[70:71]
	s_cbranch_vccnz .LBB0_1036
	v_mov_b32_e32 v2, v99
	v_mov_b32_e32 v3, v99
	v_mov_b32_e32 v4, v99
	v_mov_b32_e32 v5, v99
	s_andn2_b64 vcc, exec, s[8:9]
	s_nop 0
	v_mfma_f32_16x16x32_bf16 v[2:5], v[2:5], v[2:5], 0
	s_cbranch_vccnz .LBB0_1035
	s_barrier
	s_branch .LBB0_1035
